# merge GEMMs (128x128 tiles): LDS-DMA staging, 2x64-k swizzled ring, one barrier per K-step; first barrier uses XCD barrier
# speedup vs baseline: 1.0492x; 1.0214x over previous
; __device__ __forceinline__ int tid_opaque() { int t = threadIdx.x; asm volatile("" : "+v"(t)); return t; }
; template <int MI, int NI>
; __device__ __forceinline__ void gemm_kloop(const bf16* __restrict__ A, size_t lda, const bf16* __restrict__ Bt, size_t ldb, int K,
;                                            f16v (&acc)[MI][NI], bf16* sA, bf16* sB) {
;   const int tid = tid_opaque(), lane = tid & 63, w = tid >> 6;
;   const int r = lane & 31, hh = lane >> 5;
;   const int wm = w >> 1, wn = w & 1;
;   const int lrow = tid >> 3, lseg = tid & 7;
;   u4v ra[2 * MI], rb[2 * NI];
;   const int KT = K >> 6;
; #pragma unroll
;   for (int i = 0; i < 2 * MI; ++i) ra[i] = *(const u4v*)(A + (size_t)(lrow + 32 * i) * lda + lseg * 8);
; #pragma unroll
;   for (int i = 0; i < 2 * NI; ++i) rb[i] = *(const u4v*)(Bt + (size_t)(lrow + 32 * i) * ldb + lseg * 8);
;   unsigned pfs = 0;
;   {
;     if (tid < 64 * MI) pfs ^= *(const unsigned*)(A + (size_t)tid * lda + 64) ^ *(const unsigned*)(A + (size_t)tid * lda + 128);
;     if (tid < 64 * NI) pfs ^= *(const unsigned*)(Bt + (size_t)tid * ldb + 64) ^ *(const unsigned*)(Bt + (size_t)tid * ldb + 128);
;   }
;   for (int kt = 0; kt < KT; ++kt) {
;     __syncthreads();
; #pragma unroll
;     for (int i = 0; i < 2 * MI; ++i) *(u4v*)(sA + (lrow + 32 * i) * 72 + lseg * 8) = ra[i];
; #pragma unroll
;     for (int i = 0; i < 2 * NI; ++i) *(u4v*)(sB + (lrow + 32 * i) * 72 + lseg * 8) = rb[i];
; __device__ __forceinline__ void merge_tile(const Params& p, int mt, int nt, bf16* sA, bf16* sB) {
;     ...
;       gemm_kloop<2, 2>(p.h + (size_t)m0 * DM, DM, p.WgT + (size_t)(b * 1024 + n0) * DM, DM, DM, ag, sA, sB);
.LBB0_1067:
	v_mov_b32_e32 v16, v195
	s_lshl_b32 s36, s3, 10
	v_ashrrev_i32_e32 v2, 3, v16
	v_lshlrev_b32_e32 v0, 4, v16
	v_and_b32_e32 v0, 0x70, v0
	v_ashrrev_i32_e32 v3, 31, v2
	s_add_i32 s36, s36, s20
	v_lshl_add_u64 v[4:5], s[24:25], 0, v[0:1]
	v_lshlrev_b64 v[6:7], 11, v[2:3]
	s_mov_b64 s[40:41], 0x10000
	s_ashr_i32 s37, s36, 31
	v_lshl_add_u64 v[8:9], v[4:5], 0, v[6:7]
	v_lshl_add_u64 v[10:11], v[6:7], 0, s[40:41]
	s_mov_b64 s[40:41], 0x20000
	s_lshl_b64 s[38:39], s[36:37], 11
	v_lshl_add_u64 v[12:13], v[4:5], 0, v[10:11]
	v_lshl_add_u64 v[8:9], v[6:7], 0, s[40:41]
	s_mov_b64 s[40:41], 0x30000
	s_add_u32 s38, s12, s38
	v_lshl_add_u64 v[14:15], v[6:7], 0, s[40:41]
	s_addc_u32 s39, s13, s39
	v_lshl_add_u64 v[12:13], v[4:5], 0, v[8:9]
	v_lshl_add_u64 v[4:5], v[4:5], 0, v[14:15]
	v_lshl_add_u64 v[4:5], s[38:39], 0, v[0:1]
	v_lshl_add_u64 v[12:13], v[4:5], 0, v[6:7]
	v_lshl_add_u64 v[8:9], v[4:5], 0, v[8:9]
	v_lshl_add_u64 v[10:11], v[4:5], 0, v[10:11]
	v_lshl_add_u64 v[4:5], v[4:5], 0, v[14:15]
	v_and_b32_e32 v3, 31, v16
	v_lshrrev_b32_e32 v4, 1, v16
	s_mov_b32 s38, 0xfffffc0
	v_and_or_b32 v3, v4, s38, v3
	v_and_b32_e32 v5, 0x5f, v16
	v_and_b32_e32 v4, 16, v4
	v_mul_lo_u32 v2, v2, s33
	v_mul_lo_u32 v3, v3, s33
	v_mul_u32_u24_e32 v5, 0x90, v5
	v_or_b32_e32 v6, v6, v0
	v_lshl_add_u64 v[98:99], s[26:27], 0, v[6:7]
	v_lshl_add_u64 v[100:101], s[28:29], 0, v[6:7]
	s_mov_b64 s[38:39], 0
	v_add_u32_e32 v103, v0, v2
	v_add_u32_e32 v0, v4, v3
	v_add_u32_e32 v102, v4, v5
	v_mov_b32_e32 v2, 0
	v_mov_b32_e32 v3, v202
	v_mov_b32_e32 v4, v202
	v_mov_b32_e32 v5, v202
	v_mov_b32_e32 v6, v202
	v_mov_b32_e32 v7, v202
	v_mov_b32_e32 v8, v202
	v_mov_b32_e32 v9, v202
	v_mov_b32_e32 v10, v202
	v_mov_b32_e32 v11, v202
	v_mov_b32_e32 v12, v202
	v_mov_b32_e32 v13, v202
	v_mov_b32_e32 v14, v202
	v_mov_b32_e32 v15, v202
	v_mov_b32_e32 v16, v202
	v_mov_b32_e32 v17, v202
	v_mov_b32_e32 v18, 0
	v_mov_b32_e32 v19, v202
	v_mov_b32_e32 v20, v202
	v_mov_b32_e32 v21, v202
	v_mov_b32_e32 v22, v202
	v_mov_b32_e32 v23, v202
	v_mov_b32_e32 v24, v202
	v_mov_b32_e32 v25, v202
	v_mov_b32_e32 v26, v202
	v_mov_b32_e32 v27, v202
	v_mov_b32_e32 v28, v202
	v_mov_b32_e32 v29, v202
	v_mov_b32_e32 v30, v202
	v_mov_b32_e32 v31, v202
	v_mov_b32_e32 v32, v202
	v_mov_b32_e32 v33, v202
	v_mov_b32_e32 v34, 0
	v_mov_b32_e32 v35, v202
	v_mov_b32_e32 v36, v202
	v_mov_b32_e32 v37, v202
	v_mov_b32_e32 v38, v202
	v_mov_b32_e32 v39, v202
	v_mov_b32_e32 v40, v202
	v_mov_b32_e32 v41, v202
	v_mov_b32_e32 v42, v202
	v_mov_b32_e32 v43, v202
	v_mov_b32_e32 v44, v202
	v_mov_b32_e32 v45, v202
	v_mov_b32_e32 v46, v202
	v_mov_b32_e32 v47, v202
	v_mov_b32_e32 v48, v202
	v_mov_b32_e32 v49, v202
	v_mov_b32_e32 v66, 0
	v_mov_b32_e32 v67, v202
	v_mov_b32_e32 v68, v202
	v_mov_b32_e32 v69, v202
	v_mov_b32_e32 v70, v202
	v_mov_b32_e32 v71, v202
	v_mov_b32_e32 v72, v202
	v_mov_b32_e32 v73, v202
	v_mov_b32_e32 v74, v202
	v_mov_b32_e32 v75, v202
	v_mov_b32_e32 v76, v202
	v_mov_b32_e32 v77, v202
	v_mov_b32_e32 v78, v202
	v_mov_b32_e32 v79, v202
	v_mov_b32_e32 v80, v202
	v_mov_b32_e32 v81, v202
	v_readfirstlane_b32 s56, v98
	v_readfirstlane_b32 s57, v99
	v_readfirstlane_b32 s58, v100
	v_readfirstlane_b32 s59, v101
	v_readfirstlane_b32 s94, v195
	s_nop 3
	s_lshr_b32 s94, s94, 6
	s_mul_i32 s95, s94, 0x4000
	s_sub_u32 s56, s56, s95
	s_subb_u32 s57, s57, 0
	s_sub_u32 s58, s58, s95
	s_subb_u32 s59, s59, 0
	s_lshl_b32 s96, s94, 12
	v_and_b32_e32 v148, 63, v195
	v_lshrrev_b32_e32 v149, 3, v148
	v_lshrrev_b32_e32 v150, 4, v148
	v_and_b32_e32 v151, 7, v148
	v_xor_b32_e32 v150, v150, v151
	v_lshlrev_b32_e32 v150, 4, v150
	v_lshrrev_b32_e32 v151, 6, v195
	v_lshl_add_u32 v148, v151, 5, v149
	v_mul_u32_u24_e32 v148, 0x800, v148
	v_add_u32_e32 v136, v148, v150
	v_xor_b32_e32 v150, 64, v150
	v_add_u32_e32 v148, v148, v150
	v_add_u32_e32 v137, 0x3c00, v148
	v_add_u32_e32 v138, 0x7800, v136
	v_add_u32_e32 v139, 0xb400, v148
	v_and_b32_e32 v148, 31, v195
	v_bfe_u32 v149, v195, 5, 1
	v_bfe_u32 v150, v148, 1, 3
	v_xor_b32_e32 v149, v149, v150
	v_lshlrev_b32_e32 v149, 4, v149
	v_lshrrev_b32_e32 v150, 7, v195
	v_lshl_add_u32 v150, v150, 6, v148
	v_lshl_add_u32 v140, v150, 7, v149
	v_xor_b32_e32 v141, 32, v140
	v_xor_b32_e32 v142, 64, v140
	v_xor_b32_e32 v143, 96, v140
	v_bfe_u32 v150, v195, 6, 1
	v_lshl_add_u32 v150, v150, 6, v148
	v_lshl_add_u32 v144, v150, 7, v149
	v_add_u32_e32 v144, 16384, v144
	v_xor_b32_e32 v145, 32, v144
	v_xor_b32_e32 v146, 64, v144
	v_xor_b32_e32 v147, 96, v144
	s_barrier
	s_add_u32 m0, s96, 0
	s_nop 0
	global_load_lds_dwordx4 v136, s[56:57] offset:0
	global_load_lds_dwordx4 v137, s[56:57] offset:1024
	global_load_lds_dwordx4 v138, s[56:57] offset:2048
	global_load_lds_dwordx4 v139, s[56:57] offset:3072
	s_add_u32 m0, s96, 16384
	s_nop 0
	global_load_lds_dwordx4 v136, s[58:59] offset:0
	global_load_lds_dwordx4 v137, s[58:59] offset:1024
	global_load_lds_dwordx4 v138, s[58:59] offset:2048
	global_load_lds_dwordx4 v139, s[58:59] offset:3072
	s_add_u32 s56, s56, 128
	s_addc_u32 s57, s57, 0
	s_add_u32 s58, s58, 128
	s_addc_u32 s59, s59, 0
	s_waitcnt vmcnt(0)
	s_barrier
	s_movk_i32 s94, 7
; #define MFMA(a, b, c) __builtin_amdgcn_mfma_f32_32x32x16_bf16((a), (b), (c), 0, 0, 0)
; template <int MI, int NI>
; __device__ __forceinline__ void gemm_kloop(const bf16* __restrict__ A, size_t lda, const bf16* __restrict__ Bt, size_t ldb, int K,
;                                            f16v (&acc)[MI][NI], bf16* sA, bf16* sB) {
;     ...
;   for (int kt = 0; kt < KT; ++kt) {
;     __syncthreads();
; #pragma unroll
;     for (int i = 0; i < 2 * MI; ++i) *(u4v*)(sA + (lrow + 32 * i) * 72 + lseg * 8) = ra[i];
; #pragma unroll
;     for (int i = 0; i < 2 * NI; ++i) *(u4v*)(sB + (lrow + 32 * i) * 72 + lseg * 8) = rb[i];
;     __syncthreads();
;     if (kt + 3 < KT) {
;       const int k2 = (kt + 3) << 6;
;       if (tid < 64 * MI) pfs ^= *(const unsigned*)(A + (size_t)tid * lda + k2);
;       if (tid < 64 * NI) pfs ^= *(const unsigned*)(Bt + (size_t)tid * ldb + k2);
;     }
;     if (kt + 1 < KT) {
;       const int k0 = (kt + 1) << 6;
; #pragma unroll
;       for (int i = 0; i < 2 * MI; ++i) ra[i] = *(const u4v*)(A + (size_t)(lrow + 32 * i) * lda + k0 + lseg * 8);
; #pragma unroll
;       for (int i = 0; i < 2 * NI; ++i) rb[i] = *(const u4v*)(Bt + (size_t)(lrow + 32 * i) * ldb + k0 + lseg * 8);
;     }
; #pragma unroll
;     for (int ks = 0; ks < 4; ++ks) {
;       s8v a[MI], b[NI];
; #pragma unroll
;       for (int mi = 0; mi < MI; ++mi) a[mi] = *(const s8v*)(sA + (wm * 32 * MI + mi * 32 + r) * 72 + ks * 16 + hh * 8);
; #pragma unroll
;       for (int ni = 0; ni < NI; ++ni) b[ni] = *(const s8v*)(sB + (wn * 32 * NI + ni * 32 + r) * 72 + ks * 16 + hh * 8);
; #pragma unroll
;       for (int mi = 0; mi < MI; ++mi)
; #pragma unroll
;         for (int ni = 0; ni < NI; ++ni) acc[mi][ni] = MFMA(a[mi], b[ni], acc[mi][ni]);
;     }
.Ldma_m1_loop:
	s_add_u32 m0, s96, 32768
	s_nop 0
	global_load_lds_dwordx4 v136, s[56:57] offset:0
	global_load_lds_dwordx4 v137, s[56:57] offset:1024
	global_load_lds_dwordx4 v138, s[56:57] offset:2048
	global_load_lds_dwordx4 v139, s[56:57] offset:3072
	s_add_u32 m0, s96, 49152
	s_nop 0
	global_load_lds_dwordx4 v136, s[58:59] offset:0
	global_load_lds_dwordx4 v137, s[58:59] offset:1024
	global_load_lds_dwordx4 v138, s[58:59] offset:2048
	global_load_lds_dwordx4 v139, s[58:59] offset:3072
	s_add_u32 s56, s56, 128
	s_addc_u32 s57, s57, 0
	s_add_u32 s58, s58, 128
	s_addc_u32 s59, s59, 0
	ds_read_b128 v[104:107], v140 offset:0
	ds_read_b128 v[112:115], v144 offset:0
	ds_read_b128 v[116:119], v144 offset:4096
	ds_read_b128 v[108:111], v140 offset:4096
	ds_read_b128 v[120:123], v141 offset:0
	ds_read_b128 v[128:131], v145 offset:0
	ds_read_b128 v[132:135], v145 offset:4096
	ds_read_b128 v[124:127], v141 offset:4096
	s_waitcnt lgkmcnt(6)
	v_mfma_f32_32x32x16_bf16 v[66:81], v[104:107], v[112:115], v[66:81]
	s_waitcnt lgkmcnt(5)
	v_mfma_f32_32x32x16_bf16 v[34:49], v[104:107], v[116:119], v[34:49]
	s_waitcnt lgkmcnt(4)
	v_mfma_f32_32x32x16_bf16 v[18:33], v[108:111], v[112:115], v[18:33]
	v_mfma_f32_32x32x16_bf16 v[2:17], v[108:111], v[116:119], v[2:17]
	ds_read_b128 v[104:107], v142 offset:0
	ds_read_b128 v[112:115], v146 offset:0
	ds_read_b128 v[116:119], v146 offset:4096
	ds_read_b128 v[108:111], v142 offset:4096
	s_waitcnt lgkmcnt(6)
	v_mfma_f32_32x32x16_bf16 v[66:81], v[120:123], v[128:131], v[66:81]
	s_waitcnt lgkmcnt(5)
	v_mfma_f32_32x32x16_bf16 v[34:49], v[120:123], v[132:135], v[34:49]
	s_waitcnt lgkmcnt(4)
	v_mfma_f32_32x32x16_bf16 v[18:33], v[124:127], v[128:131], v[18:33]
	v_mfma_f32_32x32x16_bf16 v[2:17], v[124:127], v[132:135], v[2:17]
	ds_read_b128 v[120:123], v143 offset:0
	ds_read_b128 v[128:131], v147 offset:0
	ds_read_b128 v[132:135], v147 offset:4096
	ds_read_b128 v[124:127], v143 offset:4096
	s_waitcnt lgkmcnt(6)
	v_mfma_f32_32x32x16_bf16 v[66:81], v[104:107], v[112:115], v[66:81]
	s_waitcnt lgkmcnt(5)
	v_mfma_f32_32x32x16_bf16 v[34:49], v[104:107], v[116:119], v[34:49]
	s_waitcnt lgkmcnt(4)
	v_mfma_f32_32x32x16_bf16 v[18:33], v[108:111], v[112:115], v[18:33]
	v_mfma_f32_32x32x16_bf16 v[2:17], v[108:111], v[116:119], v[2:17]
	s_waitcnt lgkmcnt(2)
	v_mfma_f32_32x32x16_bf16 v[66:81], v[120:123], v[128:131], v[66:81]
	s_waitcnt lgkmcnt(1)
	v_mfma_f32_32x32x16_bf16 v[34:49], v[120:123], v[132:135], v[34:49]
	s_waitcnt lgkmcnt(0)
	v_mfma_f32_32x32x16_bf16 v[18:33], v[124:127], v[128:131], v[18:33]
	v_mfma_f32_32x32x16_bf16 v[2:17], v[124:127], v[132:135], v[2:17]
	s_waitcnt vmcnt(0)
	s_barrier
	s_add_u32 m0, s96, 0
	s_nop 0
	global_load_lds_dwordx4 v136, s[56:57] offset:0
	global_load_lds_dwordx4 v137, s[56:57] offset:1024
	global_load_lds_dwordx4 v138, s[56:57] offset:2048
	global_load_lds_dwordx4 v139, s[56:57] offset:3072
	s_add_u32 m0, s96, 16384
	s_nop 0
	global_load_lds_dwordx4 v136, s[58:59] offset:0
	global_load_lds_dwordx4 v137, s[58:59] offset:1024
	global_load_lds_dwordx4 v138, s[58:59] offset:2048
	global_load_lds_dwordx4 v139, s[58:59] offset:3072
	s_add_u32 s56, s56, 128
	s_addc_u32 s57, s57, 0
	s_add_u32 s58, s58, 128
	s_addc_u32 s59, s59, 0
	ds_read_b128 v[104:107], v140 offset:32768
	ds_read_b128 v[112:115], v144 offset:32768
	ds_read_b128 v[116:119], v144 offset:36864
	ds_read_b128 v[108:111], v140 offset:36864
	ds_read_b128 v[120:123], v141 offset:32768
	ds_read_b128 v[128:131], v145 offset:32768
	ds_read_b128 v[132:135], v145 offset:36864
	ds_read_b128 v[124:127], v141 offset:36864
	s_waitcnt lgkmcnt(6)
	v_mfma_f32_32x32x16_bf16 v[66:81], v[104:107], v[112:115], v[66:81]
	s_waitcnt lgkmcnt(5)
	v_mfma_f32_32x32x16_bf16 v[34:49], v[104:107], v[116:119], v[34:49]
	s_waitcnt lgkmcnt(4)
	v_mfma_f32_32x32x16_bf16 v[18:33], v[108:111], v[112:115], v[18:33]
	v_mfma_f32_32x32x16_bf16 v[2:17], v[108:111], v[116:119], v[2:17]
	ds_read_b128 v[104:107], v142 offset:32768
	ds_read_b128 v[112:115], v146 offset:32768
	ds_read_b128 v[116:119], v146 offset:36864
	ds_read_b128 v[108:111], v142 offset:36864
	s_waitcnt lgkmcnt(6)
	v_mfma_f32_32x32x16_bf16 v[66:81], v[120:123], v[128:131], v[66:81]
	s_waitcnt lgkmcnt(5)
	v_mfma_f32_32x32x16_bf16 v[34:49], v[120:123], v[132:135], v[34:49]
	s_waitcnt lgkmcnt(4)
	v_mfma_f32_32x32x16_bf16 v[18:33], v[124:127], v[128:131], v[18:33]
	v_mfma_f32_32x32x16_bf16 v[2:17], v[124:127], v[132:135], v[2:17]
	ds_read_b128 v[120:123], v143 offset:32768
	ds_read_b128 v[128:131], v147 offset:32768
	ds_read_b128 v[132:135], v147 offset:36864
	ds_read_b128 v[124:127], v143 offset:36864
	s_waitcnt lgkmcnt(6)
	v_mfma_f32_32x32x16_bf16 v[66:81], v[104:107], v[112:115], v[66:81]
	s_waitcnt lgkmcnt(5)
	v_mfma_f32_32x32x16_bf16 v[34:49], v[104:107], v[116:119], v[34:49]
	s_waitcnt lgkmcnt(4)
	v_mfma_f32_32x32x16_bf16 v[18:33], v[108:111], v[112:115], v[18:33]
	v_mfma_f32_32x32x16_bf16 v[2:17], v[108:111], v[116:119], v[2:17]
	s_waitcnt lgkmcnt(2)
	v_mfma_f32_32x32x16_bf16 v[66:81], v[120:123], v[128:131], v[66:81]
	s_waitcnt lgkmcnt(1)
	v_mfma_f32_32x32x16_bf16 v[34:49], v[120:123], v[132:135], v[34:49]
	s_waitcnt lgkmcnt(0)
	v_mfma_f32_32x32x16_bf16 v[18:33], v[124:127], v[128:131], v[18:33]
	v_mfma_f32_32x32x16_bf16 v[2:17], v[124:127], v[132:135], v[2:17]
	s_waitcnt vmcnt(0)
	s_barrier
; #define MFMA(a, b, c) __builtin_amdgcn_mfma_f32_32x32x16_bf16((a), (b), (c), 0, 0, 0)
; template <int MI, int NI>
; __device__ __forceinline__ void gemm_kloop(const bf16* __restrict__ A, size_t lda, const bf16* __restrict__ Bt, size_t ldb, int K,
;                                            f16v (&acc)[MI][NI], bf16* sA, bf16* sB) {
;     ...
;   for (int kt = 0; kt < KT; ++kt) {
;     __syncthreads();
; #pragma unroll
;     for (int i = 0; i < 2 * MI; ++i) *(u4v*)(sA + (lrow + 32 * i) * 72 + lseg * 8) = ra[i];
; #pragma unroll
;     for (int i = 0; i < 2 * NI; ++i) *(u4v*)(sB + (lrow + 32 * i) * 72 + lseg * 8) = rb[i];
;     __syncthreads();
;     if (kt + 3 < KT) {
;       const int k2 = (kt + 3) << 6;
;       if (tid < 64 * MI) pfs ^= *(const unsigned*)(A + (size_t)tid * lda + k2);
;       if (tid < 64 * NI) pfs ^= *(const unsigned*)(Bt + (size_t)tid * ldb + k2);
;     }
;     if (kt + 1 < KT) {
;       const int k0 = (kt + 1) << 6;
; #pragma unroll
;       for (int i = 0; i < 2 * MI; ++i) ra[i] = *(const u4v*)(A + (size_t)(lrow + 32 * i) * lda + k0 + lseg * 8);
; #pragma unroll
;       for (int i = 0; i < 2 * NI; ++i) rb[i] = *(const u4v*)(Bt + (size_t)(lrow + 32 * i) * ldb + k0 + lseg * 8);
;     }
; #pragma unroll
;     for (int ks = 0; ks < 4; ++ks) {
;       s8v a[MI], b[NI];
; #pragma unroll
;       for (int mi = 0; mi < MI; ++mi) a[mi] = *(const s8v*)(sA + (wm * 32 * MI + mi * 32 + r) * 72 + ks * 16 + hh * 8);
; #pragma unroll
;       for (int ni = 0; ni < NI; ++ni) b[ni] = *(const s8v*)(sB + (wn * 32 * NI + ni * 32 + r) * 72 + ks * 16 + hh * 8);
; #pragma unroll
;       for (int mi = 0; mi < MI; ++mi)
; #pragma unroll
;         for (int ni = 0; ni < NI; ++ni) acc[mi][ni] = MFMA(a[mi], b[ni], acc[mi][ni]);
;     }
; __device__ __forceinline__ void merge_tile(const Params& p, int mt, int nt, bf16* sA, bf16* sB) {
;     ...
;     const bf16* ya = b == 0 ? p.q : (b == 1 ? p.hv : p.gog);
	s_sub_u32 s94, s94, 1
	s_cmp_lg_u32 s94, 0
	s_cbranch_scc1 .Ldma_m1_loop
	s_add_u32 m0, s96, 32768
	s_nop 0
	global_load_lds_dwordx4 v136, s[56:57] offset:0
	global_load_lds_dwordx4 v137, s[56:57] offset:1024
	global_load_lds_dwordx4 v138, s[56:57] offset:2048
	global_load_lds_dwordx4 v139, s[56:57] offset:3072
	s_add_u32 m0, s96, 49152
	s_nop 0
	global_load_lds_dwordx4 v136, s[58:59] offset:0
	global_load_lds_dwordx4 v137, s[58:59] offset:1024
	global_load_lds_dwordx4 v138, s[58:59] offset:2048
	global_load_lds_dwordx4 v139, s[58:59] offset:3072
	s_add_u32 s56, s56, 128
	s_addc_u32 s57, s57, 0
	s_add_u32 s58, s58, 128
	s_addc_u32 s59, s59, 0
	ds_read_b128 v[104:107], v140 offset:0
	ds_read_b128 v[112:115], v144 offset:0
	ds_read_b128 v[116:119], v144 offset:4096
	ds_read_b128 v[108:111], v140 offset:4096
	ds_read_b128 v[120:123], v141 offset:0
	ds_read_b128 v[128:131], v145 offset:0
	ds_read_b128 v[132:135], v145 offset:4096
	ds_read_b128 v[124:127], v141 offset:4096
	s_waitcnt lgkmcnt(6)
	v_mfma_f32_32x32x16_bf16 v[66:81], v[104:107], v[112:115], v[66:81]
	s_waitcnt lgkmcnt(5)
	v_mfma_f32_32x32x16_bf16 v[34:49], v[104:107], v[116:119], v[34:49]
	s_waitcnt lgkmcnt(4)
	v_mfma_f32_32x32x16_bf16 v[18:33], v[108:111], v[112:115], v[18:33]
	v_mfma_f32_32x32x16_bf16 v[2:17], v[108:111], v[116:119], v[2:17]
	ds_read_b128 v[104:107], v142 offset:0
	ds_read_b128 v[112:115], v146 offset:0
	ds_read_b128 v[116:119], v146 offset:4096
	ds_read_b128 v[108:111], v142 offset:4096
	s_waitcnt lgkmcnt(6)
	v_mfma_f32_32x32x16_bf16 v[66:81], v[120:123], v[128:131], v[66:81]
	s_waitcnt lgkmcnt(5)
	v_mfma_f32_32x32x16_bf16 v[34:49], v[120:123], v[132:135], v[34:49]
	s_waitcnt lgkmcnt(4)
	v_mfma_f32_32x32x16_bf16 v[18:33], v[124:127], v[128:131], v[18:33]
	v_mfma_f32_32x32x16_bf16 v[2:17], v[124:127], v[132:135], v[2:17]
	ds_read_b128 v[120:123], v143 offset:0
	ds_read_b128 v[128:131], v147 offset:0
	ds_read_b128 v[132:135], v147 offset:4096
	ds_read_b128 v[124:127], v143 offset:4096
	s_waitcnt lgkmcnt(6)
	v_mfma_f32_32x32x16_bf16 v[66:81], v[104:107], v[112:115], v[66:81]
	s_waitcnt lgkmcnt(5)
	v_mfma_f32_32x32x16_bf16 v[34:49], v[104:107], v[116:119], v[34:49]
	s_waitcnt lgkmcnt(4)
	v_mfma_f32_32x32x16_bf16 v[18:33], v[108:111], v[112:115], v[18:33]
	v_mfma_f32_32x32x16_bf16 v[2:17], v[108:111], v[116:119], v[2:17]
	s_waitcnt lgkmcnt(2)
	v_mfma_f32_32x32x16_bf16 v[66:81], v[120:123], v[128:131], v[66:81]
	s_waitcnt lgkmcnt(1)
	v_mfma_f32_32x32x16_bf16 v[34:49], v[120:123], v[132:135], v[34:49]
	s_waitcnt lgkmcnt(0)
	v_mfma_f32_32x32x16_bf16 v[18:33], v[124:127], v[128:131], v[18:33]
	v_mfma_f32_32x32x16_bf16 v[2:17], v[124:127], v[132:135], v[2:17]
	s_waitcnt vmcnt(0)
	s_barrier
	ds_read_b128 v[104:107], v140 offset:32768
	ds_read_b128 v[112:115], v144 offset:32768
	ds_read_b128 v[116:119], v144 offset:36864
	ds_read_b128 v[108:111], v140 offset:36864
	ds_read_b128 v[120:123], v141 offset:32768
	ds_read_b128 v[128:131], v145 offset:32768
	ds_read_b128 v[132:135], v145 offset:36864
	ds_read_b128 v[124:127], v141 offset:36864
	s_waitcnt lgkmcnt(6)
	v_mfma_f32_32x32x16_bf16 v[66:81], v[104:107], v[112:115], v[66:81]
	s_waitcnt lgkmcnt(5)
	v_mfma_f32_32x32x16_bf16 v[34:49], v[104:107], v[116:119], v[34:49]
	s_waitcnt lgkmcnt(4)
	v_mfma_f32_32x32x16_bf16 v[18:33], v[108:111], v[112:115], v[18:33]
	v_mfma_f32_32x32x16_bf16 v[2:17], v[108:111], v[116:119], v[2:17]
	ds_read_b128 v[104:107], v142 offset:32768
	ds_read_b128 v[112:115], v146 offset:32768
	ds_read_b128 v[116:119], v146 offset:36864
	ds_read_b128 v[108:111], v142 offset:36864
	s_waitcnt lgkmcnt(6)
	v_mfma_f32_32x32x16_bf16 v[66:81], v[120:123], v[128:131], v[66:81]
	s_waitcnt lgkmcnt(5)
	v_mfma_f32_32x32x16_bf16 v[34:49], v[120:123], v[132:135], v[34:49]
	s_waitcnt lgkmcnt(4)
	v_mfma_f32_32x32x16_bf16 v[18:33], v[124:127], v[128:131], v[18:33]
	v_mfma_f32_32x32x16_bf16 v[2:17], v[124:127], v[132:135], v[2:17]
	ds_read_b128 v[120:123], v143 offset:32768
	ds_read_b128 v[128:131], v147 offset:32768
	ds_read_b128 v[132:135], v147 offset:36864
	ds_read_b128 v[124:127], v143 offset:36864
	s_waitcnt lgkmcnt(6)
	v_mfma_f32_32x32x16_bf16 v[66:81], v[104:107], v[112:115], v[66:81]
	s_waitcnt lgkmcnt(5)
	v_mfma_f32_32x32x16_bf16 v[34:49], v[104:107], v[116:119], v[34:49]
	s_waitcnt lgkmcnt(4)
	v_mfma_f32_32x32x16_bf16 v[18:33], v[108:111], v[112:115], v[18:33]
	v_mfma_f32_32x32x16_bf16 v[2:17], v[108:111], v[116:119], v[2:17]
	s_waitcnt lgkmcnt(2)
	v_mfma_f32_32x32x16_bf16 v[66:81], v[120:123], v[128:131], v[66:81]
	s_waitcnt lgkmcnt(1)
	v_mfma_f32_32x32x16_bf16 v[34:49], v[120:123], v[132:135], v[34:49]
	s_waitcnt lgkmcnt(0)
	v_mfma_f32_32x32x16_bf16 v[18:33], v[124:127], v[128:131], v[18:33]
	v_mfma_f32_32x32x16_bf16 v[2:17], v[124:127], v[132:135], v[2:17]
	s_nop 15
	v_readlane_b32 s38, v253, 15
	s_cmp_lt_i32 s3, 1
	v_readlane_b32 s39, v253, 16
	s_cbranch_scc1 .LBB0_1074
	s_cmp_lg_u32 s3, 1
	s_mov_b64 s[38:39], -1
	s_cbranch_scc0 .LBB0_1072
	s_mov_b64 s[38:39], 0

; __device__ __forceinline__ int tid_opaque() { int t = threadIdx.x; asm volatile("" : "+v"(t)); return t; }
; #define ZERO_ACC(acc, MI_, NI_)                 \
;   _Pragma("unroll") for (int mi = 0; mi < MI_; ++mi) \
;   _Pragma("unroll") for (int ni = 0; ni < NI_; ++ni) \
;   _Pragma("unroll") for (int e = 0; e < 16; ++e) acc[mi][ni][e] = 0.f;
; template <int MI, int NI>
; __device__ __forceinline__ void gemm_kloop(const bf16* __restrict__ A, size_t lda, const bf16* __restrict__ Bt, size_t ldb, int K,
;                                            f16v (&acc)[MI][NI], bf16* sA, bf16* sB) {
;   const int tid = tid_opaque(), lane = tid & 63, w = tid >> 6;
;   const int r = lane & 31, hh = lane >> 5;
;   const int wm = w >> 1, wn = w & 1;
;   const int lrow = tid >> 3, lseg = tid & 7;
;   u4v ra[2 * MI], rb[2 * NI];
;   const int KT = K >> 6;
; #pragma unroll
;   for (int i = 0; i < 2 * MI; ++i) ra[i] = *(const u4v*)(A + (size_t)(lrow + 32 * i) * lda + lseg * 8);
; #pragma unroll
;   for (int i = 0; i < 2 * NI; ++i) rb[i] = *(const u4v*)(Bt + (size_t)(lrow + 32 * i) * ldb + lseg * 8);
;   unsigned pfs = 0;
;   {
;     if (tid < 64 * MI) pfs ^= *(const unsigned*)(A + (size_t)tid * lda + 64) ^ *(const unsigned*)(A + (size_t)tid * lda + 128);
;     if (tid < 64 * NI) pfs ^= *(const unsigned*)(Bt + (size_t)tid * ldb + 64) ^ *(const unsigned*)(Bt + (size_t)tid * ldb + 128);
;   }
;   for (int kt = 0; kt < KT; ++kt) {
;     __syncthreads();
; #pragma unroll
;     for (int i = 0; i < 2 * MI; ++i) *(u4v*)(sA + (lrow + 32 * i) * 72 + lseg * 8) = ra[i];
; #pragma unroll
;     for (int i = 0; i < 2 * NI; ++i) *(u4v*)(sB + (lrow + 32 * i) * 72 + lseg * 8) = rb[i];
; __device__ __forceinline__ void merge_tile(const Params& p, int mt, int nt, bf16* sA, bf16* sB) {
;     ...
;     f16v ap[2][2];
;     ZERO_ACC(ap, 2, 2)
;     const bf16* ya = b == 0 ? p.q : (b == 1 ? p.hv : p.gog);
;     gemm_kloop<2, 2>(ya + (size_t)m0 * 512, 512, p.WbT + (size_t)(b * 1024 + n0) * 512, 512, 512, ap, sA, sB);
.LBB0_1074:
	s_load_dwordx2 s[38:39], s[38:39], 0x0
	v_mov_b32_e32 v64, v195
	s_waitcnt lgkmcnt(0)
	s_add_u32 s40, s38, s22
	v_ashrrev_i32_e32 v50, 3, v64
	v_lshlrev_b32_e32 v0, 4, v64
	s_addc_u32 s41, s39, s23
	v_and_b32_e32 v0, 0x70, v0
	v_ashrrev_i32_e32 v51, 31, v50
	v_lshl_add_u64 v[52:53], s[40:41], 0, v[0:1]
	v_lshlrev_b64 v[54:55], 10, v[50:51]
	s_mov_b64 s[40:41], 0x8000
	v_lshl_add_u64 v[56:57], v[52:53], 0, v[54:55]
	v_lshl_add_u64 v[58:59], v[54:55], 0, s[40:41]
	s_mov_b64 s[40:41], 0x10000
	s_lshl_b64 s[36:37], s[36:37], 10
	v_lshl_add_u64 v[60:61], v[52:53], 0, v[58:59]
	v_lshl_add_u64 v[56:57], v[54:55], 0, s[40:41]
	s_mov_b64 s[40:41], 0x18000
	s_add_u32 s36, s14, s36
	v_lshl_add_u64 v[62:63], v[54:55], 0, s[40:41]
	s_addc_u32 s37, s15, s37
	v_lshl_add_u64 v[60:61], v[52:53], 0, v[56:57]
	v_lshl_add_u64 v[52:53], v[52:53], 0, v[62:63]
	v_lshl_add_u64 v[52:53], s[36:37], 0, v[0:1]
	v_lshl_add_u64 v[60:61], v[52:53], 0, v[54:55]
	v_lshl_add_u64 v[56:57], v[52:53], 0, v[56:57]
	v_lshl_add_u64 v[58:59], v[52:53], 0, v[58:59]
	v_lshl_add_u64 v[52:53], v[52:53], 0, v[62:63]
	v_and_b32_e32 v51, 31, v64
	v_lshrrev_b32_e32 v52, 1, v64
	s_mov_b32 s36, 0xfffffc0
	v_and_or_b32 v51, v52, s36, v51
	v_and_b32_e32 v53, 0x5f, v64
	s_add_u32 s36, s38, s30
	v_and_b32_e32 v52, 16, v52
	v_mul_lo_u32 v56, v50, s33
	v_mul_lo_u32 v51, v51, s33
	v_mul_u32_u24_e32 v53, 0x90, v53
	s_addc_u32 s37, s39, s31
	v_or_b32_e32 v54, v54, v0
	v_mov_b32_e32 v50, 0
	v_lshl_add_u64 v[162:163], s[36:37], 0, v[54:55]
	v_lshl_add_u64 v[164:165], s[34:35], 0, v[54:55]
	s_mov_b64 s[36:37], 0
	v_add_u32_e32 v204, v0, v56
	v_add_u32_e32 v0, v52, v51
	v_add_u32_e32 v203, v52, v53
	v_mov_b32_e32 v51, v50
	v_mov_b32_e32 v52, v50
	v_mov_b32_e32 v53, v50
	v_mov_b32_e32 v54, v50
	v_mov_b32_e32 v55, v50
	v_mov_b32_e32 v56, v50
	v_mov_b32_e32 v57, v50
	v_mov_b32_e32 v58, v50
	v_mov_b32_e32 v59, v50
	v_mov_b32_e32 v60, v50
	v_mov_b32_e32 v61, v50
	v_mov_b32_e32 v62, v50
	v_mov_b32_e32 v63, v50
	v_mov_b32_e32 v64, v50
	v_mov_b32_e32 v65, v50
	v_mov_b32_e32 v82, v50
	v_mov_b32_e32 v83, v50
	v_mov_b32_e32 v84, v50
	v_mov_b32_e32 v85, v50
	v_mov_b32_e32 v86, v50
	v_mov_b32_e32 v87, v50
	v_mov_b32_e32 v88, v50
	v_mov_b32_e32 v89, v50
	v_mov_b32_e32 v90, v50
	v_mov_b32_e32 v91, v50
	v_mov_b32_e32 v92, v50
	v_mov_b32_e32 v93, v50
	v_mov_b32_e32 v94, v50
	v_mov_b32_e32 v95, v50
	v_mov_b32_e32 v96, v50
	v_mov_b32_e32 v97, v50
	v_mov_b32_e32 v98, v50
	v_mov_b32_e32 v99, v50
	v_mov_b32_e32 v100, v50
	v_mov_b32_e32 v101, v50
	v_mov_b32_e32 v102, v50
	v_mov_b32_e32 v103, v50
	v_mov_b32_e32 v104, v50
	v_mov_b32_e32 v105, v50
	v_mov_b32_e32 v106, v50
	v_mov_b32_e32 v107, v50
	v_mov_b32_e32 v108, v50
	v_mov_b32_e32 v109, v50
	v_mov_b32_e32 v110, v50
	v_mov_b32_e32 v111, v50
	v_mov_b32_e32 v112, v50
	v_mov_b32_e32 v113, v50
	v_mov_b32_e32 v114, v50
	v_mov_b32_e32 v115, v50
	v_mov_b32_e32 v116, v50
	v_mov_b32_e32 v117, v50
	v_mov_b32_e32 v118, v50
	v_mov_b32_e32 v119, v50
	v_mov_b32_e32 v120, v50
	v_mov_b32_e32 v121, v50
	v_mov_b32_e32 v122, v50
	v_mov_b32_e32 v123, v50
	v_mov_b32_e32 v124, v50
	v_mov_b32_e32 v125, v50
	v_mov_b32_e32 v126, v50
	v_mov_b32_e32 v127, v50
	v_mov_b32_e32 v128, v50
	v_mov_b32_e32 v129, v50
	v_readfirstlane_b32 s56, v162
	v_readfirstlane_b32 s57, v163
	v_readfirstlane_b32 s58, v164
	v_readfirstlane_b32 s59, v165
	v_readfirstlane_b32 s94, v195
	s_nop 3
	s_lshr_b32 s94, s94, 6
	s_mul_i32 s95, s94, 0x2000
	s_sub_u32 s56, s56, s95
	s_subb_u32 s57, s57, 0
	s_sub_u32 s58, s58, s95
	s_subb_u32 s59, s59, 0
	s_lshl_b32 s96, s94, 12
	v_and_b32_e32 v217, 63, v195
	v_lshrrev_b32_e32 v218, 3, v217
	v_lshrrev_b32_e32 v219, 4, v217
	v_and_b32_e32 v222, 7, v217
	v_xor_b32_e32 v219, v219, v222
	v_lshlrev_b32_e32 v219, 4, v219
	v_lshrrev_b32_e32 v222, 6, v195
	v_lshl_add_u32 v217, v222, 5, v218
	v_mul_u32_u24_e32 v217, 0x400, v217
	v_add_u32_e32 v205, v217, v219
	v_xor_b32_e32 v219, 64, v219
	v_add_u32_e32 v217, v217, v219
	v_add_u32_e32 v206, 0x1c00, v217
	v_add_u32_e32 v207, 0x3800, v205
	v_add_u32_e32 v208, 0x5400, v217
	v_and_b32_e32 v217, 31, v195
	v_bfe_u32 v218, v195, 5, 1
	v_bfe_u32 v219, v217, 1, 3
	v_xor_b32_e32 v218, v218, v219
	v_lshlrev_b32_e32 v218, 4, v218
	v_lshrrev_b32_e32 v219, 7, v195
	v_lshl_add_u32 v219, v219, 6, v217
	v_lshl_add_u32 v209, v219, 7, v218
	v_xor_b32_e32 v210, 32, v209
	v_xor_b32_e32 v211, 64, v209
	v_xor_b32_e32 v212, 96, v209
	v_bfe_u32 v219, v195, 6, 1
	v_lshl_add_u32 v219, v219, 6, v217
	v_lshl_add_u32 v213, v219, 7, v218
	v_add_u32_e32 v213, 16384, v213
	v_xor_b32_e32 v214, 32, v213
	v_xor_b32_e32 v215, 64, v213
	v_xor_b32_e32 v216, 96, v213
	s_barrier
	s_add_u32 m0, s96, 0
	s_nop 0
	global_load_lds_dwordx4 v205, s[56:57] offset:0
	global_load_lds_dwordx4 v206, s[56:57] offset:1024
	global_load_lds_dwordx4 v207, s[56:57] offset:2048
	global_load_lds_dwordx4 v208, s[56:57] offset:3072
	s_add_u32 m0, s96, 16384
	s_nop 0
	global_load_lds_dwordx4 v205, s[58:59] offset:0
	global_load_lds_dwordx4 v206, s[58:59] offset:1024
	global_load_lds_dwordx4 v207, s[58:59] offset:2048
	global_load_lds_dwordx4 v208, s[58:59] offset:3072
	s_add_u32 s56, s56, 128
	s_addc_u32 s57, s57, 0
	s_add_u32 s58, s58, 128
	s_addc_u32 s59, s59, 0
	s_waitcnt vmcnt(0)
	s_barrier
	s_movk_i32 s94, 3
; #define MFMA(a, b, c) __builtin_amdgcn_mfma_f32_32x32x16_bf16((a), (b), (c), 0, 0, 0)
; template <int MI, int NI>
; __device__ __forceinline__ void gemm_kloop(const bf16* __restrict__ A, size_t lda, const bf16* __restrict__ Bt, size_t ldb, int K,
;                                            f16v (&acc)[MI][NI], bf16* sA, bf16* sB) {
;     ...
;   for (int kt = 0; kt < KT; ++kt) {
;     __syncthreads();
; #pragma unroll
;     for (int i = 0; i < 2 * MI; ++i) *(u4v*)(sA + (lrow + 32 * i) * 72 + lseg * 8) = ra[i];
; #pragma unroll
;     for (int i = 0; i < 2 * NI; ++i) *(u4v*)(sB + (lrow + 32 * i) * 72 + lseg * 8) = rb[i];
;     __syncthreads();
;     if (kt + 3 < KT) {
;       const int k2 = (kt + 3) << 6;
;       if (tid < 64 * MI) pfs ^= *(const unsigned*)(A + (size_t)tid * lda + k2);
;       if (tid < 64 * NI) pfs ^= *(const unsigned*)(Bt + (size_t)tid * ldb + k2);
;     }
;     if (kt + 1 < KT) {
;       const int k0 = (kt + 1) << 6;
; #pragma unroll
;       for (int i = 0; i < 2 * MI; ++i) ra[i] = *(const u4v*)(A + (size_t)(lrow + 32 * i) * lda + k0 + lseg * 8);
; #pragma unroll
;       for (int i = 0; i < 2 * NI; ++i) rb[i] = *(const u4v*)(Bt + (size_t)(lrow + 32 * i) * ldb + k0 + lseg * 8);
;     }
; #pragma unroll
;     for (int ks = 0; ks < 4; ++ks) {
;       s8v a[MI], b[NI];
; #pragma unroll
;       for (int mi = 0; mi < MI; ++mi) a[mi] = *(const s8v*)(sA + (wm * 32 * MI + mi * 32 + r) * 72 + ks * 16 + hh * 8);
; #pragma unroll
;       for (int ni = 0; ni < NI; ++ni) b[ni] = *(const s8v*)(sB + (wn * 32 * NI + ni * 32 + r) * 72 + ks * 16 + hh * 8);
; #pragma unroll
;       for (int mi = 0; mi < MI; ++mi)
; #pragma unroll
;         for (int ni = 0; ni < NI; ++ni) acc[mi][ni] = MFMA(a[mi], b[ni], acc[mi][ni]);
;     }
.Ldma_m2_loop:
	s_add_u32 m0, s96, 32768
	s_nop 0
	global_load_lds_dwordx4 v205, s[56:57] offset:0
	global_load_lds_dwordx4 v206, s[56:57] offset:1024
	global_load_lds_dwordx4 v207, s[56:57] offset:2048
	global_load_lds_dwordx4 v208, s[56:57] offset:3072
	s_add_u32 m0, s96, 49152
	s_nop 0
	global_load_lds_dwordx4 v205, s[58:59] offset:0
	global_load_lds_dwordx4 v206, s[58:59] offset:1024
	global_load_lds_dwordx4 v207, s[58:59] offset:2048
	global_load_lds_dwordx4 v208, s[58:59] offset:3072
	s_add_u32 s56, s56, 128
	s_addc_u32 s57, s57, 0
	s_add_u32 s58, s58, 128
	s_addc_u32 s59, s59, 0
	ds_read_b128 v[130:133], v209 offset:0
	ds_read_b128 v[138:141], v213 offset:0
	ds_read_b128 v[142:145], v213 offset:4096
	ds_read_b128 v[134:137], v209 offset:4096
	ds_read_b128 v[146:149], v210 offset:0
	ds_read_b128 v[154:157], v214 offset:0
	ds_read_b128 v[158:161], v214 offset:4096
	ds_read_b128 v[150:153], v210 offset:4096
	s_waitcnt lgkmcnt(6)
	v_mfma_f32_32x32x16_bf16 v[114:129], v[130:133], v[138:141], v[114:129]
	s_waitcnt lgkmcnt(5)
	v_mfma_f32_32x32x16_bf16 v[98:113], v[130:133], v[142:145], v[98:113]
	s_waitcnt lgkmcnt(4)
	v_mfma_f32_32x32x16_bf16 v[82:97], v[134:137], v[138:141], v[82:97]
	v_mfma_f32_32x32x16_bf16 v[50:65], v[134:137], v[142:145], v[50:65]
	ds_read_b128 v[130:133], v211 offset:0
	ds_read_b128 v[138:141], v215 offset:0
	ds_read_b128 v[142:145], v215 offset:4096
	ds_read_b128 v[134:137], v211 offset:4096
	s_waitcnt lgkmcnt(6)
	v_mfma_f32_32x32x16_bf16 v[114:129], v[146:149], v[154:157], v[114:129]
	s_waitcnt lgkmcnt(5)
	v_mfma_f32_32x32x16_bf16 v[98:113], v[146:149], v[158:161], v[98:113]
	s_waitcnt lgkmcnt(4)
	v_mfma_f32_32x32x16_bf16 v[82:97], v[150:153], v[154:157], v[82:97]
	v_mfma_f32_32x32x16_bf16 v[50:65], v[150:153], v[158:161], v[50:65]
	ds_read_b128 v[146:149], v212 offset:0
	ds_read_b128 v[154:157], v216 offset:0
	ds_read_b128 v[158:161], v216 offset:4096
	ds_read_b128 v[150:153], v212 offset:4096
	s_waitcnt lgkmcnt(6)
	v_mfma_f32_32x32x16_bf16 v[114:129], v[130:133], v[138:141], v[114:129]
	s_waitcnt lgkmcnt(5)
	v_mfma_f32_32x32x16_bf16 v[98:113], v[130:133], v[142:145], v[98:113]
	s_waitcnt lgkmcnt(4)
	v_mfma_f32_32x32x16_bf16 v[82:97], v[134:137], v[138:141], v[82:97]
	v_mfma_f32_32x32x16_bf16 v[50:65], v[134:137], v[142:145], v[50:65]
	s_waitcnt lgkmcnt(2)
	v_mfma_f32_32x32x16_bf16 v[114:129], v[146:149], v[154:157], v[114:129]
	s_waitcnt lgkmcnt(1)
	v_mfma_f32_32x32x16_bf16 v[98:113], v[146:149], v[158:161], v[98:113]
	s_waitcnt lgkmcnt(0)
	v_mfma_f32_32x32x16_bf16 v[82:97], v[150:153], v[154:157], v[82:97]
	v_mfma_f32_32x32x16_bf16 v[50:65], v[150:153], v[158:161], v[50:65]
	s_waitcnt vmcnt(0)
	s_barrier
	s_add_u32 m0, s96, 0
	s_nop 0
	global_load_lds_dwordx4 v205, s[56:57] offset:0
	global_load_lds_dwordx4 v206, s[56:57] offset:1024
	global_load_lds_dwordx4 v207, s[56:57] offset:2048
	global_load_lds_dwordx4 v208, s[56:57] offset:3072
	s_add_u32 m0, s96, 16384
	s_nop 0
	global_load_lds_dwordx4 v205, s[58:59] offset:0
	global_load_lds_dwordx4 v206, s[58:59] offset:1024
	global_load_lds_dwordx4 v207, s[58:59] offset:2048
	global_load_lds_dwordx4 v208, s[58:59] offset:3072
	s_add_u32 s56, s56, 128
	s_addc_u32 s57, s57, 0
	s_add_u32 s58, s58, 128
	s_addc_u32 s59, s59, 0
	ds_read_b128 v[130:133], v209 offset:32768
	ds_read_b128 v[138:141], v213 offset:32768
	ds_read_b128 v[142:145], v213 offset:36864
	ds_read_b128 v[134:137], v209 offset:36864
	ds_read_b128 v[146:149], v210 offset:32768
	ds_read_b128 v[154:157], v214 offset:32768
	ds_read_b128 v[158:161], v214 offset:36864
	ds_read_b128 v[150:153], v210 offset:36864
	s_waitcnt lgkmcnt(6)
	v_mfma_f32_32x32x16_bf16 v[114:129], v[130:133], v[138:141], v[114:129]
	s_waitcnt lgkmcnt(5)
	v_mfma_f32_32x32x16_bf16 v[98:113], v[130:133], v[142:145], v[98:113]
	s_waitcnt lgkmcnt(4)
	v_mfma_f32_32x32x16_bf16 v[82:97], v[134:137], v[138:141], v[82:97]
	v_mfma_f32_32x32x16_bf16 v[50:65], v[134:137], v[142:145], v[50:65]
	ds_read_b128 v[130:133], v211 offset:32768
	ds_read_b128 v[138:141], v215 offset:32768
	ds_read_b128 v[142:145], v215 offset:36864
	ds_read_b128 v[134:137], v211 offset:36864
	s_waitcnt lgkmcnt(6)
	v_mfma_f32_32x32x16_bf16 v[114:129], v[146:149], v[154:157], v[114:129]
	s_waitcnt lgkmcnt(5)
	v_mfma_f32_32x32x16_bf16 v[98:113], v[146:149], v[158:161], v[98:113]
	s_waitcnt lgkmcnt(4)
	v_mfma_f32_32x32x16_bf16 v[82:97], v[150:153], v[154:157], v[82:97]
	v_mfma_f32_32x32x16_bf16 v[50:65], v[150:153], v[158:161], v[50:65]
	ds_read_b128 v[146:149], v212 offset:32768
	ds_read_b128 v[154:157], v216 offset:32768
	ds_read_b128 v[158:161], v216 offset:36864
	ds_read_b128 v[150:153], v212 offset:36864
	s_waitcnt lgkmcnt(6)
	v_mfma_f32_32x32x16_bf16 v[114:129], v[130:133], v[138:141], v[114:129]
	s_waitcnt lgkmcnt(5)
	v_mfma_f32_32x32x16_bf16 v[98:113], v[130:133], v[142:145], v[98:113]
	s_waitcnt lgkmcnt(4)
	v_mfma_f32_32x32x16_bf16 v[82:97], v[134:137], v[138:141], v[82:97]
	v_mfma_f32_32x32x16_bf16 v[50:65], v[134:137], v[142:145], v[50:65]
	s_waitcnt lgkmcnt(2)
	v_mfma_f32_32x32x16_bf16 v[114:129], v[146:149], v[154:157], v[114:129]
	s_waitcnt lgkmcnt(1)
	v_mfma_f32_32x32x16_bf16 v[98:113], v[146:149], v[158:161], v[98:113]
	s_waitcnt lgkmcnt(0)
	v_mfma_f32_32x32x16_bf16 v[82:97], v[150:153], v[154:157], v[82:97]
	v_mfma_f32_32x32x16_bf16 v[50:65], v[150:153], v[158:161], v[50:65]
	s_waitcnt vmcnt(0)
	s_barrier
	s_sub_u32 s94, s94, 1
	s_cmp_lg_u32 s94, 0
	s_cbranch_scc1 .Ldma_m2_loop
; #define MFMA(a, b, c) __builtin_amdgcn_mfma_f32_32x32x16_bf16((a), (b), (c), 0, 0, 0)
; template <int MI, int NI>
; __device__ __forceinline__ void gemm_kloop(const bf16* __restrict__ A, size_t lda, const bf16* __restrict__ Bt, size_t ldb, int K,
;                                            f16v (&acc)[MI][NI], bf16* sA, bf16* sB) {
;     ...
;   for (int kt = 0; kt < KT; ++kt) {
;     __syncthreads();
; #pragma unroll
;     for (int i = 0; i < 2 * MI; ++i) *(u4v*)(sA + (lrow + 32 * i) * 72 + lseg * 8) = ra[i];
; #pragma unroll
;     for (int i = 0; i < 2 * NI; ++i) *(u4v*)(sB + (lrow + 32 * i) * 72 + lseg * 8) = rb[i];
;     __syncthreads();
;     if (kt + 3 < KT) {
;       const int k2 = (kt + 3) << 6;
;       if (tid < 64 * MI) pfs ^= *(const unsigned*)(A + (size_t)tid * lda + k2);
;       if (tid < 64 * NI) pfs ^= *(const unsigned*)(Bt + (size_t)tid * ldb + k2);
;     }
;     if (kt + 1 < KT) {
;       const int k0 = (kt + 1) << 6;
; #pragma unroll
;       for (int i = 0; i < 2 * MI; ++i) ra[i] = *(const u4v*)(A + (size_t)(lrow + 32 * i) * lda + k0 + lseg * 8);
; #pragma unroll
;       for (int i = 0; i < 2 * NI; ++i) rb[i] = *(const u4v*)(Bt + (size_t)(lrow + 32 * i) * ldb + k0 + lseg * 8);
;     }
; #pragma unroll
;     for (int ks = 0; ks < 4; ++ks) {
;       s8v a[MI], b[NI];
; #pragma unroll
;       for (int mi = 0; mi < MI; ++mi) a[mi] = *(const s8v*)(sA + (wm * 32 * MI + mi * 32 + r) * 72 + ks * 16 + hh * 8);
; #pragma unroll
;       for (int ni = 0; ni < NI; ++ni) b[ni] = *(const s8v*)(sB + (wn * 32 * NI + ni * 32 + r) * 72 + ks * 16 + hh * 8);
; #pragma unroll
;       for (int mi = 0; mi < MI; ++mi)
; #pragma unroll
;         for (int ni = 0; ni < NI; ++ni) acc[mi][ni] = MFMA(a[mi], b[ni], acc[mi][ni]);
;     }
	s_add_u32 m0, s96, 32768
	s_nop 0
	global_load_lds_dwordx4 v205, s[56:57] offset:0
	global_load_lds_dwordx4 v206, s[56:57] offset:1024
	global_load_lds_dwordx4 v207, s[56:57] offset:2048
	global_load_lds_dwordx4 v208, s[56:57] offset:3072
	s_add_u32 m0, s96, 49152
	s_nop 0
	global_load_lds_dwordx4 v205, s[58:59] offset:0
	global_load_lds_dwordx4 v206, s[58:59] offset:1024
	global_load_lds_dwordx4 v207, s[58:59] offset:2048
	global_load_lds_dwordx4 v208, s[58:59] offset:3072
	s_add_u32 s56, s56, 128
	s_addc_u32 s57, s57, 0
	s_add_u32 s58, s58, 128
	s_addc_u32 s59, s59, 0
	ds_read_b128 v[130:133], v209 offset:0
	ds_read_b128 v[138:141], v213 offset:0
	ds_read_b128 v[142:145], v213 offset:4096
	ds_read_b128 v[134:137], v209 offset:4096
	ds_read_b128 v[146:149], v210 offset:0
	ds_read_b128 v[154:157], v214 offset:0
	ds_read_b128 v[158:161], v214 offset:4096
	ds_read_b128 v[150:153], v210 offset:4096
	s_waitcnt lgkmcnt(6)
	v_mfma_f32_32x32x16_bf16 v[114:129], v[130:133], v[138:141], v[114:129]
	s_waitcnt lgkmcnt(5)
	v_mfma_f32_32x32x16_bf16 v[98:113], v[130:133], v[142:145], v[98:113]
	s_waitcnt lgkmcnt(4)
	v_mfma_f32_32x32x16_bf16 v[82:97], v[134:137], v[138:141], v[82:97]
	v_mfma_f32_32x32x16_bf16 v[50:65], v[134:137], v[142:145], v[50:65]
	ds_read_b128 v[130:133], v211 offset:0
	ds_read_b128 v[138:141], v215 offset:0
	ds_read_b128 v[142:145], v215 offset:4096
	ds_read_b128 v[134:137], v211 offset:4096
	s_waitcnt lgkmcnt(6)
	v_mfma_f32_32x32x16_bf16 v[114:129], v[146:149], v[154:157], v[114:129]
	s_waitcnt lgkmcnt(5)
	v_mfma_f32_32x32x16_bf16 v[98:113], v[146:149], v[158:161], v[98:113]
	s_waitcnt lgkmcnt(4)
	v_mfma_f32_32x32x16_bf16 v[82:97], v[150:153], v[154:157], v[82:97]
	v_mfma_f32_32x32x16_bf16 v[50:65], v[150:153], v[158:161], v[50:65]
	ds_read_b128 v[146:149], v212 offset:0
	ds_read_b128 v[154:157], v216 offset:0
	ds_read_b128 v[158:161], v216 offset:4096
	ds_read_b128 v[150:153], v212 offset:4096
	s_waitcnt lgkmcnt(6)
	v_mfma_f32_32x32x16_bf16 v[114:129], v[130:133], v[138:141], v[114:129]
	s_waitcnt lgkmcnt(5)
	v_mfma_f32_32x32x16_bf16 v[98:113], v[130:133], v[142:145], v[98:113]
	s_waitcnt lgkmcnt(4)
	v_mfma_f32_32x32x16_bf16 v[82:97], v[134:137], v[138:141], v[82:97]
	v_mfma_f32_32x32x16_bf16 v[50:65], v[134:137], v[142:145], v[50:65]
	s_waitcnt lgkmcnt(2)
	v_mfma_f32_32x32x16_bf16 v[114:129], v[146:149], v[154:157], v[114:129]
	s_waitcnt lgkmcnt(1)
	v_mfma_f32_32x32x16_bf16 v[98:113], v[146:149], v[158:161], v[98:113]
	s_waitcnt lgkmcnt(0)
	v_mfma_f32_32x32x16_bf16 v[82:97], v[150:153], v[154:157], v[82:97]
	v_mfma_f32_32x32x16_bf16 v[50:65], v[150:153], v[158:161], v[50:65]
	s_waitcnt vmcnt(0)
	s_barrier
	ds_read_b128 v[130:133], v209 offset:32768
	ds_read_b128 v[138:141], v213 offset:32768
	ds_read_b128 v[142:145], v213 offset:36864
	ds_read_b128 v[134:137], v209 offset:36864
	ds_read_b128 v[146:149], v210 offset:32768
	ds_read_b128 v[154:157], v214 offset:32768
	ds_read_b128 v[158:161], v214 offset:36864
	ds_read_b128 v[150:153], v210 offset:36864
	s_waitcnt lgkmcnt(6)
	v_mfma_f32_32x32x16_bf16 v[114:129], v[130:133], v[138:141], v[114:129]
	s_waitcnt lgkmcnt(5)
	v_mfma_f32_32x32x16_bf16 v[98:113], v[130:133], v[142:145], v[98:113]
	s_waitcnt lgkmcnt(4)
	v_mfma_f32_32x32x16_bf16 v[82:97], v[134:137], v[138:141], v[82:97]
	v_mfma_f32_32x32x16_bf16 v[50:65], v[134:137], v[142:145], v[50:65]
	ds_read_b128 v[130:133], v211 offset:32768
	ds_read_b128 v[138:141], v215 offset:32768
	ds_read_b128 v[142:145], v215 offset:36864
	ds_read_b128 v[134:137], v211 offset:36864
	s_waitcnt lgkmcnt(6)
	v_mfma_f32_32x32x16_bf16 v[114:129], v[146:149], v[154:157], v[114:129]
	s_waitcnt lgkmcnt(5)
	v_mfma_f32_32x32x16_bf16 v[98:113], v[146:149], v[158:161], v[98:113]
	s_waitcnt lgkmcnt(4)
	v_mfma_f32_32x32x16_bf16 v[82:97], v[150:153], v[154:157], v[82:97]
	v_mfma_f32_32x32x16_bf16 v[50:65], v[150:153], v[158:161], v[50:65]
	ds_read_b128 v[146:149], v212 offset:32768
	ds_read_b128 v[154:157], v216 offset:32768
	ds_read_b128 v[158:161], v216 offset:36864
	ds_read_b128 v[150:153], v212 offset:36864
	s_waitcnt lgkmcnt(6)
	v_mfma_f32_32x32x16_bf16 v[114:129], v[130:133], v[138:141], v[114:129]
	s_waitcnt lgkmcnt(5)
	v_mfma_f32_32x32x16_bf16 v[98:113], v[130:133], v[142:145], v[98:113]
	s_waitcnt lgkmcnt(4)
	v_mfma_f32_32x32x16_bf16 v[82:97], v[134:137], v[138:141], v[82:97]
	v_mfma_f32_32x32x16_bf16 v[50:65], v[134:137], v[142:145], v[50:65]
	s_waitcnt lgkmcnt(2)
	v_mfma_f32_32x32x16_bf16 v[114:129], v[146:149], v[154:157], v[114:129]
	s_waitcnt lgkmcnt(1)
	v_mfma_f32_32x32x16_bf16 v[98:113], v[146:149], v[158:161], v[98:113]
	s_waitcnt lgkmcnt(0)
; #define MFMA(a, b, c) __builtin_amdgcn_mfma_f32_32x32x16_bf16((a), (b), (c), 0, 0, 0)
; __device__ __forceinline__ unsigned pack2(float a, float b) { f2_t f = {a, b}; return __builtin_bit_cast(unsigned, __builtin_convertvector(f, bf2_t)); }
; __device__ __forceinline__ float sigmoidf_(float x) { return __builtin_amdgcn_rcpf(1.f + fexp(-x)); }
; template <int MI, int NI>
; __device__ __forceinline__ void gemm_kloop(const bf16* __restrict__ A, size_t lda, const bf16* __restrict__ Bt, size_t ldb, int K,
;                                            f16v (&acc)[MI][NI], bf16* sA, bf16* sB) {
;     ...
;     for (int ks = 0; ks < 4; ++ks) {
;       s8v a[MI], b[NI];
; #pragma unroll
;       for (int mi = 0; mi < MI; ++mi) a[mi] = *(const s8v*)(sA + (wm * 32 * MI + mi * 32 + r) * 72 + ks * 16 + hh * 8);
; #pragma unroll
;       for (int ni = 0; ni < NI; ++ni) b[ni] = *(const s8v*)(sB + (wn * 32 * NI + ni * 32 + r) * 72 + ks * 16 + hh * 8);
; #pragma unroll
;       for (int mi = 0; mi < MI; ++mi)
; #pragma unroll
;         for (int ni = 0; ni < NI; ++ni) acc[mi][ni] = MFMA(a[mi], b[ni], acc[mi][ni]);
;     }
; __device__ __forceinline__ void merge_tile(const Params& p, int mt, int nt, bf16* sA, bf16* sB) {
;     ...
;           for (int e = 0; e < 8; ++e) sg[mi][ni][e] = pack2(sigmoidf_(ag[mi][ni][2 * e]), sigmoidf_(ag[mi][ni][2 * e + 1]));
	v_mfma_f32_32x32x16_bf16 v[82:97], v[150:153], v[154:157], v[82:97]
	v_mfma_f32_32x32x16_bf16 v[50:65], v[150:153], v[158:161], v[50:65]
	s_nop 15
	v_mul_f32_e32 v36, 0xbfb8aa3b, v36
	v_mul_f32_e32 v37, 0xbfb8aa3b, v37
	v_mul_f32_e32 v66, 0xbfb8aa3b, v66
	v_mul_f32_e32 v67, 0xbfb8aa3b, v67
	v_exp_f32_e32 v36, v36
	v_exp_f32_e32 v37, v37
	v_exp_f32_e32 v66, v66
	v_exp_f32_e32 v67, v67
	v_add_f32_e32 v36, 1.0, v36
	v_add_f32_e32 v37, 1.0, v37
	v_mul_f32_e32 v38, 0xbfb8aa3b, v38
	v_mul_f32_e32 v39, 0xbfb8aa3b, v39
	v_add_f32_e32 v66, 1.0, v66
	v_add_f32_e32 v67, 1.0, v67
	v_mul_f32_e32 v68, 0xbfb8aa3b, v68
	v_mul_f32_e32 v69, 0xbfb8aa3b, v69
	v_rcp_f32_e32 v36, v36
	v_rcp_f32_e32 v37, v37
	v_exp_f32_e32 v38, v38
	v_exp_f32_e32 v39, v39
	v_rcp_f32_e32 v66, v66
	v_rcp_f32_e32 v67, v67
	v_exp_f32_e32 v68, v68
	v_exp_f32_e32 v69, v69
	v_cvt_pk_bf16_f32 v36, v36, v37
	v_add_f32_e32 v37, 1.0, v38
	v_add_f32_e32 v38, 1.0, v39
	v_mul_f32_e32 v39, 0xbfb8aa3b, v40
	v_mul_f32_e32 v40, 0xbfb8aa3b, v41
	v_cvt_pk_bf16_f32 v66, v66, v67
	v_add_f32_e32 v67, 1.0, v68
	v_add_f32_e32 v68, 1.0, v69
	v_mul_f32_e32 v69, 0xbfb8aa3b, v70
	v_mul_f32_e32 v70, 0xbfb8aa3b, v71
	v_rcp_f32_e32 v37, v37
	v_rcp_f32_e32 v38, v38
	v_exp_f32_e32 v39, v39
	v_exp_f32_e32 v40, v40
	v_rcp_f32_e32 v67, v67
	v_rcp_f32_e32 v68, v68
	v_exp_f32_e32 v69, v69
	v_exp_f32_e32 v70, v70
	v_cvt_pk_bf16_f32 v37, v37, v38
	v_add_f32_e32 v38, 1.0, v39
	v_add_f32_e32 v39, 1.0, v40
	v_mul_f32_e32 v40, 0xbfb8aa3b, v42
	v_mul_f32_e32 v41, 0xbfb8aa3b, v43
	v_cvt_pk_bf16_f32 v67, v67, v68
	v_add_f32_e32 v68, 1.0, v69
	v_add_f32_e32 v69, 1.0, v70
	v_mul_f32_e32 v70, 0xbfb8aa3b, v72
	v_mul_f32_e32 v71, 0xbfb8aa3b, v73
	v_rcp_f32_e32 v38, v38
	v_rcp_f32_e32 v39, v39
	v_exp_f32_e32 v40, v40
	v_exp_f32_e32 v41, v41
	v_rcp_f32_e32 v68, v68
	v_rcp_f32_e32 v69, v69
	v_exp_f32_e32 v70, v70
	v_exp_f32_e32 v71, v71
	v_cvt_pk_bf16_f32 v38, v38, v39
	v_add_f32_e32 v39, 1.0, v40
	v_add_f32_e32 v40, 1.0, v41
	v_mul_f32_e32 v41, 0xbfb8aa3b, v44
	v_mul_f32_e32 v42, 0xbfb8aa3b, v45
	v_cvt_pk_bf16_f32 v68, v68, v69
	v_add_f32_e32 v69, 1.0, v70
	v_add_f32_e32 v70, 1.0, v71
	v_mul_f32_e32 v71, 0xbfb8aa3b, v74
	v_mul_f32_e32 v72, 0xbfb8aa3b, v75
	v_rcp_f32_e32 v39, v39
	v_rcp_f32_e32 v40, v40
	v_exp_f32_e32 v41, v41
	v_exp_f32_e32 v42, v42
	v_rcp_f32_e32 v69, v69
	v_rcp_f32_e32 v70, v70
	v_exp_f32_e32 v71, v71
	v_exp_f32_e32 v72, v72
	v_mul_f32_e32 v20, 0xbfb8aa3b, v20
	v_mul_f32_e32 v21, 0xbfb8aa3b, v21
	v_cvt_pk_bf16_f32 v39, v39, v40
	v_add_f32_e32 v40, 1.0, v41
	v_add_f32_e32 v41, 1.0, v42
	v_mul_f32_e32 v42, 0xbfb8aa3b, v46
	v_mul_f32_e32 v43, 0xbfb8aa3b, v47
	v_exp_f32_e32 v20, v20
	v_exp_f32_e32 v21, v21
	v_cvt_pk_bf16_f32 v69, v69, v70
	v_add_f32_e32 v70, 1.0, v71
	v_add_f32_e32 v71, 1.0, v72
	v_mul_f32_e32 v72, 0xbfb8aa3b, v76
	v_mul_f32_e32 v73, 0xbfb8aa3b, v77
	v_rcp_f32_e32 v40, v40
	v_rcp_f32_e32 v41, v41
	v_exp_f32_e32 v42, v42
	v_exp_f32_e32 v43, v43
	v_rcp_f32_e32 v70, v70
	v_rcp_f32_e32 v71, v71
	v_exp_f32_e32 v72, v72
	v_exp_f32_e32 v73, v73
	v_add_f32_e32 v20, 1.0, v20
	v_add_f32_e32 v21, 1.0, v21
	v_mul_f32_e32 v22, 0xbfb8aa3b, v22
	v_mul_f32_e32 v23, 0xbfb8aa3b, v23
	v_cvt_pk_bf16_f32 v40, v40, v41
	v_add_f32_e32 v41, 1.0, v42
	v_add_f32_e32 v42, 1.0, v43
	v_mul_f32_e32 v43, 0xbfb8aa3b, v48
	v_mul_f32_e32 v44, 0xbfb8aa3b, v49
	v_rcp_f32_e32 v20, v20
	v_rcp_f32_e32 v21, v21
	v_exp_f32_e32 v22, v22
	v_exp_f32_e32 v23, v23
	v_cvt_pk_bf16_f32 v70, v70, v71
	v_add_f32_e32 v71, 1.0, v72
	v_add_f32_e32 v72, 1.0, v73
	v_mul_f32_e32 v73, 0xbfb8aa3b, v78
	v_mul_f32_e32 v74, 0xbfb8aa3b, v79
	v_rcp_f32_e32 v41, v41
	v_rcp_f32_e32 v42, v42
	v_exp_f32_e32 v43, v43
	v_exp_f32_e32 v44, v44
	v_rcp_f32_e32 v71, v71
	v_rcp_f32_e32 v72, v72
	v_exp_f32_e32 v73, v73
	v_exp_f32_e32 v74, v74
	v_mul_f32_e32 v18, 0xbfb8aa3b, v18
	v_cvt_pk_bf16_f32 v20, v20, v21
	v_add_f32_e32 v21, 1.0, v22
	v_add_f32_e32 v22, 1.0, v23
	v_mul_f32_e32 v23, 0xbfb8aa3b, v24
	v_mul_f32_e32 v24, 0xbfb8aa3b, v25
	v_cvt_pk_bf16_f32 v41, v41, v42
	v_add_f32_e32 v42, 1.0, v43
	v_add_f32_e32 v43, 1.0, v44
	v_exp_f32_e32 v44, v18
	v_mul_f32_e32 v18, 0xbfb8aa3b, v19
	v_rcp_f32_e32 v21, v21
	v_rcp_f32_e32 v22, v22
	v_exp_f32_e32 v23, v23
	v_exp_f32_e32 v24, v24
	v_cvt_pk_bf16_f32 v71, v71, v72
	v_add_f32_e32 v72, 1.0, v73
	v_add_f32_e32 v73, 1.0, v74
	v_mul_f32_e32 v74, 0xbfb8aa3b, v80
	v_mul_f32_e32 v75, 0xbfb8aa3b, v81
	v_rcp_f32_e32 v42, v42
	v_rcp_f32_e32 v43, v43
	v_exp_f32_e32 v19, v18
	v_rcp_f32_e32 v72, v72
	v_rcp_f32_e32 v73, v73
	v_exp_f32_e32 v74, v74
	v_exp_f32_e32 v75, v75
	v_cvt_pk_bf16_f32 v21, v21, v22
	v_add_f32_e32 v22, 1.0, v23
	v_add_f32_e32 v23, 1.0, v24
	v_mul_f32_e32 v24, 0xbfb8aa3b, v26
	v_mul_f32_e32 v25, 0xbfb8aa3b, v27
	v_mul_f32_e32 v34, 0xbfb8aa3b, v34
	v_cvt_pk_bf16_f32 v18, v42, v43
	v_add_f32_e32 v42, 1.0, v44
	v_add_f32_e32 v19, 1.0, v19
	v_rcp_f32_e32 v22, v22
	v_rcp_f32_e32 v23, v23
	v_exp_f32_e32 v24, v24
	v_exp_f32_e32 v25, v25
	v_cvt_pk_bf16_f32 v72, v72, v73
	v_add_f32_e32 v73, 1.0, v74
	v_add_f32_e32 v74, 1.0, v75
	v_exp_f32_e32 v75, v34
	v_mul_f32_e32 v34, 0xbfb8aa3b, v35
	v_rcp_f32_e32 v42, v42
	v_rcp_f32_e32 v19, v19
	v_rcp_f32_e32 v73, v73
	v_rcp_f32_e32 v74, v74
	v_exp_f32_e32 v35, v34
	v_cvt_pk_bf16_f32 v22, v22, v23
	v_add_f32_e32 v23, 1.0, v24
	v_add_f32_e32 v24, 1.0, v25
	v_cvt_pk_bf16_f32 v19, v42, v19
	v_rcp_f32_e32 v42, v24
	v_mul_f32_e32 v24, 0xbfb8aa3b, v28
	v_cvt_pk_bf16_f32 v34, v73, v74
	v_add_f32_e32 v73, 1.0, v75
	v_add_f32_e32 v35, 1.0, v35
	v_exp_f32_e32 v28, v24
	v_rcp_f32_e32 v73, v73
	v_rcp_f32_e32 v35, v35
	v_rcp_f32_e32 v23, v23
	v_add_f32_e32 v28, 1.0, v28
	v_cvt_pk_bf16_f32 v35, v73, v35
; __device__ __forceinline__ unsigned pack2(float a, float b) { f2_t f = {a, b}; return __builtin_bit_cast(unsigned, __builtin_convertvector(f, bf2_t)); }
; __device__ __forceinline__ float sigmoidf_(float x) { return __builtin_amdgcn_rcpf(1.f + fexp(-x)); }
; #define ZERO_ACC(acc, MI_, NI_)                 \
;   _Pragma("unroll") for (int mi = 0; mi < MI_; ++mi) \
;   _Pragma("unroll") for (int ni = 0; ni < NI_; ++ni) \
;   _Pragma("unroll") for (int e = 0; e < 16; ++e) acc[mi][ni][e] = 0.f;
; __device__ __forceinline__ void merge_tile(const Params& p, int mt, int nt, bf16* sA, bf16* sB) {
;     ...
;       for (int mi = 0; mi < 2; ++mi)
; #pragma unroll
;         for (int ni = 0; ni < 2; ++ni)
; #pragma unroll
;           for (int e = 0; e < 8; ++e) sg[mi][ni][e] = pack2(sigmoidf_(ag[mi][ni][2 * e]), sigmoidf_(ag[mi][ni][2 * e + 1]));
;     }
;     f16v ap[2][2];
;     ZERO_ACC(ap, 2, 2)
;     const bf16* ya = b == 0 ? p.q : (b == 1 ? p.hv : p.gog);
;     gemm_kloop<2, 2>(ya + (size_t)m0 * 512, 512, p.WbT + (size_t)(b * 1024 + n0) * 512, 512, 512, ap, sA, sB);
; #pragma unroll
;     for (int mi = 0; mi < 2; ++mi)
; #pragma unroll
;       for (int ni = 0; ni < 2; ++ni)
; #pragma unroll
;         for (int e = 0; e < 8; ++e) {
;           const float v0 = __uint_as_float(mg[mi][ni][e] << 16) + __uint_as_float(sg[mi][ni][e] << 16) * ap[mi][ni][2 * e];
;           const float v1 = __uint_as_float(mg[mi][ni][e] & 0xffff0000u) + __uint_as_float(sg[mi][ni][e] & 0xffff0000u) * ap[mi][ni][2 * e + 1];
;           mg[mi][ni][e] = pack2(v0, v1);
;         }
	v_rcp_f32_e32 v73, v28
	v_mul_f32_e32 v28, 0xbfb8aa3b, v29
	v_exp_f32_e32 v28, v28
	v_cvt_pk_bf16_f32 v23, v23, v42
	v_add_f32_e32 v134, 1.0, v28
	v_mul_f32_e32 v28, 0xbfb8aa3b, v30
	v_mul_f32_e32 v32, 0xbfb8aa3b, v32
	v_mul_f32_e32 v33, 0xbfb8aa3b, v33
	v_exp_f32_e32 v135, v28
	v_mul_f32_e32 v136, 0xbfb8aa3b, v31
	v_exp_f32_e32 v32, v32
	v_exp_f32_e32 v33, v33
	v_mul_f32_e32 v2, 0xbfb8aa3b, v2
	v_add_f32_e32 v32, 1.0, v32
	v_exp_f32_e32 v2, v2
	v_mul_f32_e32 v3, 0xbfb8aa3b, v3
	v_exp_f32_e32 v3, v3
	v_rcp_f32_e32 v134, v134
	v_add_f32_e32 v2, 1.0, v2
	v_mul_f32_e32 v12, 0xbfb8aa3b, v12
	v_add_f32_e32 v29, 1.0, v33
	v_rcp_f32_e32 v28, v32
	v_rcp_f32_e32 v29, v29
	v_cvt_pk_bf16_f32 v73, v73, v134
	s_add_i32 s3, s3, 1
	s_add_u32 s28, s28, 0x200000
	v_cvt_pk_bf16_f32 v32, v28, v29
	v_rcp_f32_e32 v28, v2
	v_add_f32_e32 v2, 1.0, v3
	v_mul_f32_e32 v3, 0xbfb8aa3b, v4
	v_exp_f32_e32 v3, v3
	v_mul_f32_e32 v4, 0xbfb8aa3b, v5
	v_exp_f32_e32 v4, v4
	v_rcp_f32_e32 v29, v2
	v_add_f32_e32 v2, 1.0, v3
	v_mul_f32_e32 v3, 0xbfb8aa3b, v6
	v_rcp_f32_e32 v30, v2
	v_exp_f32_e32 v24, v136
	v_add_f32_e32 v25, 1.0, v135
	v_rcp_f32_e32 v135, v25
	v_add_f32_e32 v2, 1.0, v4
	v_add_f32_e32 v24, 1.0, v24
	v_rcp_f32_e32 v136, v24
	v_exp_f32_e32 v3, v3
	v_mul_f32_e32 v4, 0xbfb8aa3b, v7
	v_exp_f32_e32 v4, v4
	v_rcp_f32_e32 v6, v2
	v_add_f32_e32 v2, 1.0, v3
	v_rcp_f32_e32 v7, v2
	v_add_f32_e32 v31, 1.0, v4
	v_rcp_f32_e32 v31, v31
	v_cvt_pk_bf16_f32 v33, v28, v29
	v_cvt_pk_bf16_f32 v78, v30, v6
	v_mul_f32_e32 v6, 0xbfb8aa3b, v8
	v_cvt_pk_bf16_f32 v79, v7, v31
	v_exp_f32_e32 v80, v6
	v_mul_f32_e32 v6, 0xbfb8aa3b, v9
	v_exp_f32_e32 v81, v6
	v_cvt_pk_bf16_f32 v134, v135, v136
	s_addc_u32 s29, s29, 0
	s_add_u32 s34, s34, 0x100000
	s_addc_u32 s35, s35, 0
	s_cmp_lg_u32 s3, 3
	v_add_f32_e32 v2, 1.0, v80
	v_rcp_f32_e32 v80, v2
	v_add_f32_e32 v2, 1.0, v81
	v_rcp_f32_e32 v81, v2
	v_mul_f32_e32 v2, 0xbfb8aa3b, v10
	v_exp_f32_e32 v10, v2
	v_mul_f32_e32 v0, 0xbfb8aa3b, v11
	v_exp_f32_e32 v0, v0
	v_add_f32_e32 v10, 1.0, v10
	v_rcp_f32_e32 v10, v10
	v_cvt_pk_bf16_f32 v11, v80, v81
	v_add_f32_e32 v0, 1.0, v0
	v_rcp_f32_e32 v0, v0
	v_mul_f32_e32 v7, 0xbfb8aa3b, v13
	v_exp_f32_e32 v6, v12
	v_exp_f32_e32 v7, v7
	v_mul_f32_e32 v8, 0xbfb8aa3b, v14
	v_mul_f32_e32 v9, 0xbfb8aa3b, v15
	v_exp_f32_e32 v8, v8
	v_exp_f32_e32 v9, v9
	v_mul_f32_e32 v12, 0xbfb8aa3b, v16
	v_mul_f32_e32 v13, 0xbfb8aa3b, v17
	v_add_f32_e32 v6, 1.0, v6
	v_add_f32_e32 v7, 1.0, v7
	v_exp_f32_e32 v12, v12
	v_exp_f32_e32 v13, v13
	v_rcp_f32_e32 v6, v6
	v_rcp_f32_e32 v7, v7
	v_add_f32_e32 v8, 1.0, v8
	v_add_f32_e32 v9, 1.0, v9
	v_rcp_f32_e32 v8, v8
	v_rcp_f32_e32 v9, v9
	v_cvt_pk_bf16_f32 v0, v10, v0
	v_add_f32_e32 v12, 1.0, v12
	v_lshlrev_b32_e32 v2, 16, v201
	v_lshlrev_b32_e32 v4, 16, v66
	v_and_b32_e32 v3, 0xffff0000, v201
	v_and_b32_e32 v5, 0xffff0000, v66
	v_fma_f32 v2, v114, v4, v2
	v_fma_f32 v3, v115, v5, v3
	v_lshlrev_b32_e32 v4, 16, v67
	v_cvt_pk_bf16_f32 v201, v2, v3
	v_lshlrev_b32_e32 v2, 16, v200
	v_and_b32_e32 v3, 0xffff0000, v200
	v_and_b32_e32 v5, 0xffff0000, v67
	v_pk_fma_f32 v[2:3], v[116:117], v[4:5], v[2:3]
	v_lshlrev_b32_e32 v4, 16, v68
	v_cvt_pk_bf16_f32 v200, v2, v3
	v_lshlrev_b32_e32 v2, 16, v199
	v_and_b32_e32 v3, 0xffff0000, v199
	v_and_b32_e32 v5, 0xffff0000, v68
	v_pk_fma_f32 v[2:3], v[118:119], v[4:5], v[2:3]
	v_lshlrev_b32_e32 v4, 16, v69
	v_cvt_pk_bf16_f32 v199, v2, v3
	v_lshlrev_b32_e32 v2, 16, v196
	v_and_b32_e32 v3, 0xffff0000, v196
	v_and_b32_e32 v5, 0xffff0000, v69
	v_pk_fma_f32 v[2:3], v[120:121], v[4:5], v[2:3]
	v_lshlrev_b32_e32 v4, 16, v70
	v_cvt_pk_bf16_f32 v196, v2, v3
	v_lshlrev_b32_e32 v2, 16, v193
	v_and_b32_e32 v3, 0xffff0000, v193
	v_and_b32_e32 v5, 0xffff0000, v70
	v_fma_f32 v2, v122, v4, v2
	v_fma_f32 v3, v123, v5, v3
	v_lshlrev_b32_e32 v4, 16, v71
	v_cvt_pk_bf16_f32 v193, v2, v3
	v_lshlrev_b32_e32 v2, 16, v192
	v_and_b32_e32 v3, 0xffff0000, v192
	v_and_b32_e32 v5, 0xffff0000, v71
	v_pk_fma_f32 v[2:3], v[124:125], v[4:5], v[2:3]
	v_lshlrev_b32_e32 v4, 16, v72
	v_cvt_pk_bf16_f32 v192, v2, v3
	v_lshlrev_b32_e32 v2, 16, v191
	v_and_b32_e32 v3, 0xffff0000, v191
	v_and_b32_e32 v5, 0xffff0000, v72
	v_pk_fma_f32 v[2:3], v[126:127], v[4:5], v[2:3]
	v_lshlrev_b32_e32 v4, 16, v34
	v_cvt_pk_bf16_f32 v191, v2, v3
	v_lshlrev_b32_e32 v2, 16, v190
	v_and_b32_e32 v3, 0xffff0000, v190
	v_and_b32_e32 v5, 0xffff0000, v34
	v_pk_fma_f32 v[2:3], v[128:129], v[4:5], v[2:3]
	v_lshlrev_b32_e32 v4, 16, v35
	v_cvt_pk_bf16_f32 v190, v2, v3
	v_lshlrev_b32_e32 v2, 16, v187
	v_and_b32_e32 v3, 0xffff0000, v187
	v_and_b32_e32 v5, 0xffff0000, v35
	v_pk_fma_f32 v[2:3], v[98:99], v[4:5], v[2:3]
	v_lshlrev_b32_e32 v4, 16, v36
	v_cvt_pk_bf16_f32 v187, v2, v3
	v_lshlrev_b32_e32 v2, 16, v189
	v_and_b32_e32 v3, 0xffff0000, v189
	v_and_b32_e32 v5, 0xffff0000, v36
	v_pk_fma_f32 v[2:3], v[100:101], v[4:5], v[2:3]
	v_lshlrev_b32_e32 v4, 16, v37
	v_cvt_pk_bf16_f32 v189, v2, v3
	v_lshlrev_b32_e32 v2, 16, v188
	v_and_b32_e32 v3, 0xffff0000, v188
	v_and_b32_e32 v5, 0xffff0000, v37
	v_pk_fma_f32 v[2:3], v[102:103], v[4:5], v[2:3]
	v_lshlrev_b32_e32 v4, 16, v38
	v_cvt_pk_bf16_f32 v188, v2, v3
	v_lshlrev_b32_e32 v2, 16, v186
	v_and_b32_e32 v3, 0xffff0000, v186
	v_and_b32_e32 v5, 0xffff0000, v38
	v_pk_fma_f32 v[2:3], v[104:105], v[4:5], v[2:3]
	v_lshlrev_b32_e32 v4, 16, v39
	v_cvt_pk_bf16_f32 v186, v2, v3
	v_lshlrev_b32_e32 v2, 16, v185
	v_and_b32_e32 v3, 0xffff0000, v185
	v_and_b32_e32 v5, 0xffff0000, v39
	v_pk_fma_f32 v[2:3], v[106:107], v[4:5], v[2:3]
	v_lshlrev_b32_e32 v4, 16, v40
	v_cvt_pk_bf16_f32 v185, v2, v3
	v_lshlrev_b32_e32 v2, 16, v184
	v_and_b32_e32 v3, 0xffff0000, v184
	v_and_b32_e32 v5, 0xffff0000, v40
; __device__ __forceinline__ unsigned pack2(float a, float b) { f2_t f = {a, b}; return __builtin_bit_cast(unsigned, __builtin_convertvector(f, bf2_t)); }
; __device__ __forceinline__ void merge_tile(const Params& p, int mt, int nt, bf16* sA, bf16* sB) {
;     ...
; #pragma unroll
;     for (int mi = 0; mi < 2; ++mi)
; #pragma unroll
;       for (int ni = 0; ni < 2; ++ni)
; #pragma unroll
;         for (int e = 0; e < 8; ++e) {
;           const float v0 = __uint_as_float(mg[mi][ni][e] << 16) + __uint_as_float(sg[mi][ni][e] << 16) * ap[mi][ni][2 * e];
;           const float v1 = __uint_as_float(mg[mi][ni][e] & 0xffff0000u) + __uint_as_float(sg[mi][ni][e] & 0xffff0000u) * ap[mi][ni][2 * e + 1];
;           mg[mi][ni][e] = pack2(v0, v1);
;         }
;   }
; #pragma unroll
;   for (int mi = 0; mi < 2; ++mi)
; #pragma unroll
;     for (int ni = 0; ni < 2; ++ni)
; #pragma unroll
;       for (int e = 0; e < 16; ++e) {
;         const int t = m0 + wm * 64 + mi * 32 + ROW_OF(e, hh);
;         p.merged[(size_t)t * DM + n0 + wn * 64 + ni * 32 + r] = (bf16)((e & 1) ? (mg[mi][ni][e >> 1] >> 16) : (mg[mi][ni][e >> 1] & 0xffffu));
;       }
	v_pk_fma_f32 v[2:3], v[108:109], v[4:5], v[2:3]
	v_lshlrev_b32_e32 v4, 16, v41
	v_cvt_pk_bf16_f32 v184, v2, v3
	v_lshlrev_b32_e32 v2, 16, v183
	v_and_b32_e32 v3, 0xffff0000, v183
	v_and_b32_e32 v5, 0xffff0000, v41
	v_pk_fma_f32 v[2:3], v[110:111], v[4:5], v[2:3]
	v_lshlrev_b32_e32 v4, 16, v18
	v_cvt_pk_bf16_f32 v183, v2, v3
	v_lshlrev_b32_e32 v2, 16, v182
	v_and_b32_e32 v3, 0xffff0000, v182
	v_and_b32_e32 v5, 0xffff0000, v18
	v_pk_fma_f32 v[2:3], v[112:113], v[4:5], v[2:3]
	v_lshlrev_b32_e32 v4, 16, v19
	v_cvt_pk_bf16_f32 v182, v2, v3
	v_lshlrev_b32_e32 v2, 16, v181
	v_and_b32_e32 v3, 0xffff0000, v181
	v_and_b32_e32 v5, 0xffff0000, v19
	v_pk_fma_f32 v[2:3], v[82:83], v[4:5], v[2:3]
	v_lshlrev_b32_e32 v4, 16, v20
	v_cvt_pk_bf16_f32 v181, v2, v3
	v_lshlrev_b32_e32 v2, 16, v180
	v_and_b32_e32 v3, 0xffff0000, v180
	v_and_b32_e32 v5, 0xffff0000, v20
	v_pk_fma_f32 v[2:3], v[84:85], v[4:5], v[2:3]
	v_lshlrev_b32_e32 v4, 16, v21
	v_cvt_pk_bf16_f32 v180, v2, v3
	v_lshlrev_b32_e32 v2, 16, v179
	v_and_b32_e32 v3, 0xffff0000, v179
	v_and_b32_e32 v5, 0xffff0000, v21
	v_pk_fma_f32 v[2:3], v[86:87], v[4:5], v[2:3]
	v_lshlrev_b32_e32 v4, 16, v22
	v_cvt_pk_bf16_f32 v179, v2, v3
	v_lshlrev_b32_e32 v2, 16, v178
	v_and_b32_e32 v3, 0xffff0000, v178
	v_and_b32_e32 v5, 0xffff0000, v22
	v_pk_fma_f32 v[2:3], v[88:89], v[4:5], v[2:3]
	v_lshlrev_b32_e32 v4, 16, v23
	v_cvt_pk_bf16_f32 v178, v2, v3
	v_lshlrev_b32_e32 v2, 16, v177
	v_and_b32_e32 v3, 0xffff0000, v177
	v_and_b32_e32 v5, 0xffff0000, v23
	v_pk_fma_f32 v[2:3], v[90:91], v[4:5], v[2:3]
	v_lshlrev_b32_e32 v4, 16, v73
	v_cvt_pk_bf16_f32 v177, v2, v3
	v_lshlrev_b32_e32 v2, 16, v176
	v_and_b32_e32 v3, 0xffff0000, v176
	v_and_b32_e32 v5, 0xffff0000, v73
	v_pk_fma_f32 v[2:3], v[92:93], v[4:5], v[2:3]
	v_lshlrev_b32_e32 v4, 16, v134
	v_cvt_pk_bf16_f32 v176, v2, v3
	v_lshlrev_b32_e32 v2, 16, v175
	v_and_b32_e32 v3, 0xffff0000, v175
	v_and_b32_e32 v5, 0xffff0000, v134
	v_pk_fma_f32 v[2:3], v[94:95], v[4:5], v[2:3]
	v_lshlrev_b32_e32 v4, 16, v32
	v_cvt_pk_bf16_f32 v175, v2, v3
	v_lshlrev_b32_e32 v2, 16, v174
	v_and_b32_e32 v3, 0xffff0000, v174
	v_and_b32_e32 v5, 0xffff0000, v32
	v_pk_fma_f32 v[2:3], v[96:97], v[4:5], v[2:3]
	v_lshlrev_b32_e32 v4, 16, v33
	v_cvt_pk_bf16_f32 v174, v2, v3
	v_lshlrev_b32_e32 v2, 16, v170
	v_and_b32_e32 v3, 0xffff0000, v170
	v_and_b32_e32 v5, 0xffff0000, v33
	v_pk_fma_f32 v[2:3], v[50:51], v[4:5], v[2:3]
	v_lshlrev_b32_e32 v4, 16, v78
	v_cvt_pk_bf16_f32 v170, v2, v3
	v_lshlrev_b32_e32 v2, 16, v172
	v_and_b32_e32 v3, 0xffff0000, v172
	v_and_b32_e32 v5, 0xffff0000, v78
	v_pk_fma_f32 v[2:3], v[52:53], v[4:5], v[2:3]
	v_lshlrev_b32_e32 v4, 16, v79
	v_cvt_pk_bf16_f32 v172, v2, v3
	v_lshlrev_b32_e32 v2, 16, v171
	v_and_b32_e32 v3, 0xffff0000, v171
	v_and_b32_e32 v5, 0xffff0000, v79
	v_pk_fma_f32 v[2:3], v[54:55], v[4:5], v[2:3]
	v_lshlrev_b32_e32 v4, 16, v11
	v_cvt_pk_bf16_f32 v171, v2, v3
	v_lshlrev_b32_e32 v2, 16, v169
	v_and_b32_e32 v3, 0xffff0000, v169
	v_and_b32_e32 v5, 0xffff0000, v11
	v_pk_fma_f32 v[2:3], v[56:57], v[4:5], v[2:3]
	v_add_f32_e32 v13, 1.0, v13
	v_cvt_pk_bf16_f32 v169, v2, v3
	v_lshlrev_b32_e32 v2, 16, v168
	v_lshlrev_b32_e32 v4, 16, v0
	v_and_b32_e32 v3, 0xffff0000, v168
	v_and_b32_e32 v5, 0xffff0000, v0
	v_rcp_f32_e32 v12, v12
	v_rcp_f32_e32 v13, v13
	v_cvt_pk_bf16_f32 v6, v6, v7
	v_pk_fma_f32 v[2:3], v[58:59], v[4:5], v[2:3]
	v_lshlrev_b32_e32 v4, 16, v6
	v_cvt_pk_bf16_f32 v168, v2, v3
	v_lshlrev_b32_e32 v2, 16, v167
	v_and_b32_e32 v3, 0xffff0000, v167
	v_and_b32_e32 v5, 0xffff0000, v6
	v_cvt_pk_bf16_f32 v7, v8, v9
	v_pk_fma_f32 v[2:3], v[60:61], v[4:5], v[2:3]
	v_lshlrev_b32_e32 v4, 16, v7
	v_cvt_pk_bf16_f32 v167, v2, v3
	v_lshlrev_b32_e32 v2, 16, v166
	v_and_b32_e32 v3, 0xffff0000, v166
	v_and_b32_e32 v5, 0xffff0000, v7
	v_cvt_pk_bf16_f32 v8, v12, v13
	v_pk_fma_f32 v[2:3], v[62:63], v[4:5], v[2:3]
	v_lshlrev_b32_e32 v4, 16, v8
	v_cvt_pk_bf16_f32 v166, v2, v3
	v_lshlrev_b32_e32 v2, 16, v173
	v_and_b32_e32 v3, 0xffff0000, v173
	v_and_b32_e32 v5, 0xffff0000, v8
	v_pk_fma_f32 v[2:3], v[64:65], v[4:5], v[2:3]
	s_nop 0
	v_cvt_pk_bf16_f32 v173, v2, v3
	s_cbranch_scc1 .LBB0_1067
	v_lshrrev_b32_e32 v4, 3, v197
	v_ashrrev_i32_e32 v2, 1, v198
	v_and_or_b32 v4, v4, 4, s2
	s_lshl_b64 s[2:3], s[20:21], 1
	v_readlane_b32 s20, v252, 15
	v_and_b32_e32 v2, 0xffffffc0, v2
	v_readlane_b32 s26, v252, 21
	v_and_b32_e32 v0, 64, v198
	v_add_u32_e32 v2, v4, v2
	v_readlane_b32 s27, v252, 22
	s_add_u32 s2, s26, s2
	v_and_b32_e32 v3, 31, v197
	s_addc_u32 s3, s27, s3
	v_lshlrev_b32_e32 v0, 1, v0
	v_or_b32_e32 v8, 1, v2
	v_or_b32_e32 v10, 2, v2
	v_or_b32_e32 v12, 3, v2
	v_or_b32_e32 v14, 8, v2
	v_or_b32_e32 v16, 9, v2
	v_or_b32_e32 v18, 10, v2
	v_or_b32_e32 v20, 11, v2
	v_or_b32_e32 v22, 16, v2
	v_or_b32_e32 v24, 17, v2
	v_or_b32_e32 v26, 18, v2
	v_or_b32_e32 v28, 19, v2
	v_or_b32_e32 v30, 24, v2
	v_or_b32_e32 v32, 25, v2
	v_or_b32_e32 v34, 26, v2
	v_or_b32_e32 v36, 27, v2
	v_lshl_add_u64 v[4:5], s[2:3], 0, v[0:1]
	v_lshlrev_b32_e32 v0, 1, v3
	v_ashrrev_i32_e32 v3, 31, v2
	v_ashrrev_i32_e32 v9, 31, v8
	v_ashrrev_i32_e32 v11, 31, v10
	v_ashrrev_i32_e32 v13, 31, v12
	v_ashrrev_i32_e32 v15, 31, v14
	v_ashrrev_i32_e32 v17, 31, v16
	v_ashrrev_i32_e32 v19, 31, v18
	v_ashrrev_i32_e32 v21, 31, v20
	v_ashrrev_i32_e32 v23, 31, v22
	v_ashrrev_i32_e32 v25, 31, v24
	v_ashrrev_i32_e32 v27, 31, v26
	v_ashrrev_i32_e32 v29, 31, v28
	v_ashrrev_i32_e32 v31, 31, v30
	v_ashrrev_i32_e32 v33, 31, v32
	v_ashrrev_i32_e32 v35, 31, v34
	v_ashrrev_i32_e32 v37, 31, v36
	v_lshl_add_u64 v[4:5], v[4:5], 0, v[0:1]
	v_lshlrev_b64 v[6:7], 11, v[2:3]
	v_lshlrev_b64 v[8:9], 11, v[8:9]
	v_lshlrev_b64 v[10:11], 11, v[10:11]
; __device__ __forceinline__ void merge_tile(const Params& p, int mt, int nt, bf16* sA, bf16* sB) {
;     ...
; #pragma unroll
;   for (int mi = 0; mi < 2; ++mi)
; #pragma unroll
;     for (int ni = 0; ni < 2; ++ni)
; #pragma unroll
;       for (int e = 0; e < 16; ++e) {
;         const int t = m0 + wm * 64 + mi * 32 + ROW_OF(e, hh);
;         p.merged[(size_t)t * DM + n0 + wn * 64 + ni * 32 + r] = (bf16)((e & 1) ? (mg[mi][ni][e >> 1] >> 16) : (mg[mi][ni][e >> 1] & 0xffffu));
;       }
	v_lshlrev_b64 v[12:13], 11, v[12:13]
	v_lshlrev_b64 v[14:15], 11, v[14:15]
	v_lshlrev_b64 v[16:17], 11, v[16:17]
	v_lshlrev_b64 v[18:19], 11, v[18:19]
	v_lshlrev_b64 v[20:21], 11, v[20:21]
	v_lshlrev_b64 v[22:23], 11, v[22:23]
	v_lshlrev_b64 v[24:25], 11, v[24:25]
	v_lshlrev_b64 v[26:27], 11, v[26:27]
	v_lshlrev_b64 v[28:29], 11, v[28:29]
	v_lshlrev_b64 v[30:31], 11, v[30:31]
	v_lshlrev_b64 v[32:33], 11, v[32:33]
	v_lshlrev_b64 v[34:35], 11, v[34:35]
	v_lshlrev_b64 v[36:37], 11, v[36:37]
	v_lshl_add_u64 v[6:7], v[4:5], 0, v[6:7]
	v_lshl_add_u64 v[8:9], v[4:5], 0, v[8:9]
	v_lshl_add_u64 v[10:11], v[4:5], 0, v[10:11]
	v_lshl_add_u64 v[12:13], v[4:5], 0, v[12:13]
	v_lshl_add_u64 v[14:15], v[4:5], 0, v[14:15]
	v_lshl_add_u64 v[16:17], v[4:5], 0, v[16:17]
	v_lshl_add_u64 v[18:19], v[4:5], 0, v[18:19]
	v_lshl_add_u64 v[20:21], v[4:5], 0, v[20:21]
	v_lshl_add_u64 v[22:23], v[4:5], 0, v[22:23]
	v_lshl_add_u64 v[24:25], v[4:5], 0, v[24:25]
	v_lshl_add_u64 v[26:27], v[4:5], 0, v[26:27]
	v_lshl_add_u64 v[28:29], v[4:5], 0, v[28:29]
	v_lshl_add_u64 v[30:31], v[4:5], 0, v[30:31]
	v_lshl_add_u64 v[32:33], v[4:5], 0, v[32:33]
	v_lshl_add_u64 v[34:35], v[4:5], 0, v[34:35]
	v_lshl_add_u64 v[36:37], v[4:5], 0, v[36:37]
	global_store_short v[6:7], v201, off
	global_store_short_d16_hi v[8:9], v201, off
	global_store_short v[10:11], v200, off
	global_store_short_d16_hi v[12:13], v200, off
	global_store_short v[14:15], v199, off
	global_store_short_d16_hi v[16:17], v199, off
	global_store_short v[18:19], v196, off
	global_store_short_d16_hi v[20:21], v196, off
	global_store_short v[22:23], v193, off
	global_store_short_d16_hi v[24:25], v193, off
	global_store_short v[26:27], v192, off
	global_store_short_d16_hi v[28:29], v192, off
	global_store_short v[30:31], v191, off
	global_store_short_d16_hi v[32:33], v191, off
	global_store_short v[34:35], v190, off
	global_store_short_d16_hi v[36:37], v190, off
	global_store_short v[6:7], v187, off offset:64
	global_store_short_d16_hi v[8:9], v187, off offset:64
	global_store_short v[10:11], v189, off offset:64
	global_store_short_d16_hi v[12:13], v189, off offset:64
	global_store_short v[14:15], v188, off offset:64
	global_store_short_d16_hi v[16:17], v188, off offset:64
	global_store_short v[18:19], v186, off offset:64
	global_store_short_d16_hi v[20:21], v186, off offset:64
	global_store_short v[22:23], v185, off offset:64
	global_store_short_d16_hi v[24:25], v185, off offset:64
	global_store_short v[26:27], v184, off offset:64
	global_store_short_d16_hi v[28:29], v184, off offset:64
	global_store_short v[30:31], v183, off offset:64
	global_store_short_d16_hi v[32:33], v183, off offset:64
	global_store_short v[34:35], v182, off offset:64
	global_store_short_d16_hi v[36:37], v182, off offset:64
	v_or_b32_e32 v6, 32, v2
	v_or_b32_e32 v8, 33, v2
	v_or_b32_e32 v10, 34, v2
	v_or_b32_e32 v12, 35, v2
	v_or_b32_e32 v14, 40, v2
	v_or_b32_e32 v16, 41, v2
	v_or_b32_e32 v18, 42, v2
	v_or_b32_e32 v20, 43, v2
	v_or_b32_e32 v22, 48, v2
	v_or_b32_e32 v24, 49, v2
	v_or_b32_e32 v26, 50, v2
	v_or_b32_e32 v28, 51, v2
	v_or_b32_e32 v30, 56, v2
	v_or_b32_e32 v32, 57, v2
	v_or_b32_e32 v34, 58, v2
	v_or_b32_e32 v2, 59, v2
	v_ashrrev_i32_e32 v7, 31, v6
	v_ashrrev_i32_e32 v9, 31, v8
	v_ashrrev_i32_e32 v11, 31, v10
	v_ashrrev_i32_e32 v13, 31, v12
	v_ashrrev_i32_e32 v15, 31, v14
	v_ashrrev_i32_e32 v17, 31, v16
	v_ashrrev_i32_e32 v19, 31, v18
	v_ashrrev_i32_e32 v21, 31, v20
	v_ashrrev_i32_e32 v23, 31, v22
	v_ashrrev_i32_e32 v25, 31, v24
	v_ashrrev_i32_e32 v27, 31, v26
	v_ashrrev_i32_e32 v29, 31, v28
	v_ashrrev_i32_e32 v31, 31, v30
	v_ashrrev_i32_e32 v33, 31, v32
	v_ashrrev_i32_e32 v35, 31, v34
	v_ashrrev_i32_e32 v3, 31, v2
	v_readlane_b32 s2, v254, 60
	v_lshlrev_b64 v[6:7], 11, v[6:7]
	v_lshlrev_b64 v[8:9], 11, v[8:9]
	v_lshlrev_b64 v[10:11], 11, v[10:11]
	v_lshlrev_b64 v[12:13], 11, v[12:13]
	v_lshlrev_b64 v[14:15], 11, v[14:15]
	v_lshlrev_b64 v[16:17], 11, v[16:17]
	v_lshlrev_b64 v[18:19], 11, v[18:19]
	v_lshlrev_b64 v[20:21], 11, v[20:21]
	v_lshlrev_b64 v[22:23], 11, v[22:23]
	v_lshlrev_b64 v[24:25], 11, v[24:25]
	v_lshlrev_b64 v[26:27], 11, v[26:27]
	v_lshlrev_b64 v[28:29], 11, v[28:29]
	v_lshlrev_b64 v[30:31], 11, v[30:31]
	v_lshlrev_b64 v[32:33], 11, v[32:33]
	v_lshlrev_b64 v[34:35], 11, v[34:35]
	v_lshlrev_b64 v[2:3], 11, v[2:3]
	s_add_i32 s0, s0, s2
	v_lshl_add_u64 v[6:7], v[4:5], 0, v[6:7]
	v_lshl_add_u64 v[8:9], v[4:5], 0, v[8:9]
	v_lshl_add_u64 v[10:11], v[4:5], 0, v[10:11]
	v_lshl_add_u64 v[12:13], v[4:5], 0, v[12:13]
	v_lshl_add_u64 v[14:15], v[4:5], 0, v[14:15]
	v_lshl_add_u64 v[16:17], v[4:5], 0, v[16:17]
	v_lshl_add_u64 v[18:19], v[4:5], 0, v[18:19]
	v_lshl_add_u64 v[20:21], v[4:5], 0, v[20:21]
	v_lshl_add_u64 v[22:23], v[4:5], 0, v[22:23]
	v_lshl_add_u64 v[24:25], v[4:5], 0, v[24:25]
	v_lshl_add_u64 v[26:27], v[4:5], 0, v[26:27]
	v_lshl_add_u64 v[28:29], v[4:5], 0, v[28:29]
	v_lshl_add_u64 v[30:31], v[4:5], 0, v[30:31]
	v_lshl_add_u64 v[32:33], v[4:5], 0, v[32:33]
	v_lshl_add_u64 v[34:35], v[4:5], 0, v[34:35]
	v_lshl_add_u64 v[2:3], v[4:5], 0, v[2:3]
	s_cmpk_gt_u32 s0, 0xff
	v_readlane_b32 s21, v252, 16
	v_readlane_b32 s22, v252, 17
	v_readlane_b32 s23, v252, 18
	v_readlane_b32 s24, v252, 19
	v_readlane_b32 s25, v252, 20
	global_store_short v[6:7], v181, off
	global_store_short_d16_hi v[8:9], v181, off
	global_store_short v[10:11], v180, off
	global_store_short_d16_hi v[12:13], v180, off
	global_store_short v[14:15], v179, off
	global_store_short_d16_hi v[16:17], v179, off
	global_store_short v[18:19], v178, off
	global_store_short_d16_hi v[20:21], v178, off
	global_store_short v[22:23], v177, off
	global_store_short_d16_hi v[24:25], v177, off
	global_store_short v[26:27], v176, off
	global_store_short_d16_hi v[28:29], v176, off
	global_store_short v[30:31], v175, off
	global_store_short_d16_hi v[32:33], v175, off
	global_store_short v[34:35], v174, off
	global_store_short_d16_hi v[2:3], v174, off
	global_store_short v[6:7], v170, off offset:64
	global_store_short_d16_hi v[8:9], v170, off offset:64
	global_store_short v[10:11], v172, off offset:64
	global_store_short_d16_hi v[12:13], v172, off offset:64
	global_store_short v[14:15], v171, off offset:64
	global_store_short_d16_hi v[16:17], v171, off offset:64
	global_store_short v[18:19], v169, off offset:64
	global_store_short_d16_hi v[20:21], v169, off offset:64
	global_store_short v[22:23], v168, off offset:64
	global_store_short_d16_hi v[24:25], v168, off offset:64
	global_store_short v[26:27], v167, off offset:64
	global_store_short_d16_hi v[28:29], v167, off offset:64
	global_store_short v[30:31], v166, off offset:64
	global_store_short_d16_hi v[32:33], v166, off offset:64
	global_store_short v[34:35], v173, off offset:64
	global_store_short_d16_hi v[2:3], v173, off offset:64
	s_cbranch_scc0 .LBB0_1066

; __device__ __forceinline__ void xcd_barrier(const XcdBarrier& b) {
;     asm volatile("s_waitcnt vmcnt(0)" ::: "memory");
;     __syncthreads();
;     if (threadIdx.x == 0) {
;         unsigned* bar = b.bar;
;         __builtin_amdgcn_s_waitcnt(0);
;         unsigned nloc = b.st[0], nx = b.st[1];
;         if (nloc == 0u) { xcd_barrier_complete(bar, b.x, nloc, nx); b.st[0] = nloc; b.st[1] = nx; }
; __global__ void __launch_bounds__(256, 2) mk(Params p, int ph_lo, int ph_hi, int coop) {
;     ...
;     if (coop && ph + 1 < ph_hi) {
;       if (ph == ph_lo) cg::this_grid().sync();
;       else xcd_barrier(xb);
;     }
.LBB0_1922:
	v_readlane_b32 s20, v252, 4
	s_add_i32 s0, s63, 1
	v_readlane_b32 s21, v252, 5
	s_cmp_lt_i32 s0, s21
	v_readlane_b32 s20, v253, 21
	s_cselect_b64 s[2:3], -1, 0
	v_readlane_b32 s21, v253, 22
	s_and_b64 s[2:3], s[20:21], s[2:3]
	s_andn2_b64 vcc, exec, s[2:3]
	v_readlane_b32 s22, v252, 6
	v_readlane_b32 s23, v252, 7
	s_cbranch_vccnz .LBB0_1989
	v_readlane_b32 s20, v252, 4
	s_cmp_lg_u32 s63, s20
	s_mov_b64 s[2:3], -1
	v_readlane_b32 s21, v252, 5
	v_readlane_b32 s22, v252, 6
	v_readlane_b32 s23, v252, 7
	s_waitcnt vmcnt(0)
	s_waitcnt vmcnt(63) expcnt(7) lgkmcnt(15)
	s_barrier
	s_mov_b64 s[2:3], exec
	v_readlane_b32 s20, v252, 2
	v_readlane_b32 s21, v252, 3
	s_and_b64 s[20:21], s[2:3], s[20:21]
	s_mov_b64 exec, s[20:21]
	s_cbranch_execz .LBB0_1976
	v_mov_b32_e32 v0, 0x12000
	s_waitcnt vmcnt(0) expcnt(0) lgkmcnt(0)
	ds_read_b32 v3, v0
	v_mov_b32_e32 v0, 0x12004
	ds_read_b32 v2, v0
	s_waitcnt lgkmcnt(1)
	v_cmp_ne_u32_e32 vcc, 0, v3
	s_cbranch_vccnz .LBB0_1940
	v_readlane_b32 s22, v252, 9
	v_readlane_b32 s23, v252, 10
	s_load_dwordx2 s[20:21], s[22:23], 0x0
	s_nop 0
	s_load_dword s22, s[22:23], 0x8
	s_mov_b32 s27, 1
	s_waitcnt lgkmcnt(0)
	s_mul_i32 s26, s21, s20
	s_mul_i32 s26, s26, s22
	s_branch .LBB0_1928
